# attention (FoX + DSA) K tile LDS swizzle widened from 3 to 4 XOR bits: K-fragment ds_read_b128 bank-conflict free; +128 immediate replaced by v_xor of bit 7
# speedup vs baseline: 1.0028x; 1.0008x over previous
; #define VMW() asm volatile("s_waitcnt vmcnt(0)" ::: "memory")
; template <int MODE>
; __device__ __forceinline__ void prime(const Ref& cur, char* lds, Seam& S) {
;     constexpr int PKV = MODE == 0 ? 2048 : 512;
;     const int tid = threadIdx.x, wid = __builtin_amdgcn_readfirstlane(tid >> 6), lane = tid & 63, r32 = lane & 31, hi = lane >> 5;
;     const int sr = tid >> 4, sc = (tid & 15) * 8, kws = KSWZ(sr, sc * 2); char* K_lds = lds + 2 * SHM_V;
;     const bf16_t* qp = cur.Q + qrow_off<MODE>(wid * QBLK + r32) + hi * 8;
; #pragma unroll
;     for (int d0 = 0; d0 < 8; ++d0) S.qr[d0] = LD8(qp + d0 * 16);
;     SLOAD_H(cur.K, cur.V, 0); VMW(); SWRITE_HK(0);
;     __syncthreads();
; }
; template <int MODE>
; __device__ __forceinline__ void block(const Ref& cur, const Ref& nxt, char* lds, Seam& S) {
;     constexpr int PKV = MODE == 0 ? 2048 : 512;
;     const int tid = threadIdx.x, wid = __builtin_amdgcn_readfirstlane(tid >> 6), lane = tid & 63, r32 = lane & 31, hi = lane >> 5;
;     const int NT = cur.NT;
;     const int qlo = cur.P0 + wid * QBLK, qm = qlo + r32 - 4 * hi;
;     char* V_lds = lds; char* K_lds = lds + 2 * SHM_V;
;     float* ws = (float*)(lds + 2 * SHM_V + 2 * SHM_K) + wid * 64; float* li_l = ws, * al_l = ws + 32;
;     float m_reg = -1e30f, l_reg = 0; f32x16 o[4] = {};
;     const int sr = tid >> 4, sc = (tid & 15) * 8, vst0 = v_st(sr, sc), vst1 = v_st(32 + sr, sc), kws = KSWZ(sr, sc * 2);
;     const int vb0 = (int)(uintptr_t)V_lds + v_rd_base(lane);
; __device__ __forceinline__ fa::Ref fox_ref(int L, bf16_t* RD, const float* biasK, float thr, int lane) {
;     const int qb = 15 - (L >> 6), bh = L & 63, b = bh >> 4, h = bh & 15; fa::Ref r;
;     const size_t base = (size_t)b * SEQ * 2048 + (size_t)h * 128;
;     const float* bp = biasK + (size_t)bh * SEQ; const int t0 = qb * 256, nj = qb * 4;
;     const float bt = bp[t0], bj = bp[64 * (lane < nj ? lane : 0) + 63];
;     const unsigned long long sk = __ballot(lane < nj && (bt - bj) * SM_SCALE > thr);
;     const int T0 = sk == ~0ull ? 64 : __builtin_ctzll(~sk);
;     r.Q = RD + base + (size_t)qb * 256 * 2048; r.O = RD + base + (size_t)qb * 256 * 2048;
;     r.K = RD + (size_t)M * 2048 + base + (size_t)T0 * 64 * 2048; r.V = RD + (size_t)2 * M * 2048 + base + (size_t)T0 * 64 * 2048;
;     r.bias = bp + T0 * 64; r.msk = nullptr; r.P0 = t0 - T0 * 64; r.NT = (qb + 1) * 4 - T0; return r;
.LBB0_520:
	s_or_b64 exec, exec, s[4:5]
	s_add_u32 s11, s84, 0x1a800000
	s_addc_u32 s12, s85, 0
	s_lshl_b32 s1, s9, 7
	s_lshl_b32 s4, s10, 19
	v_cndmask_b32_e64 v2, 0, 1, s[6:7]
	s_and_b32 s1, s1, 0x780
	s_and_b32 s4, s4, 0x1800000
	v_cmp_ne_u32_e32 vcc, 0, v2
	s_or_b32 s1, s4, s1
	s_not_b64 s[4:5], vcc
	s_ff1_i32_b64 s4, s[4:5]
	s_min_u32 s6, s4, 64
	s_lshl_b32 s1, s1, 1
	s_mov_b32 s73, 0
	s_add_u32 s7, s11, s1
	s_addc_u32 s9, s12, 0
	s_lshl_b64 s[4:5], s[72:73], 20
	s_add_u32 s10, s7, s4
	v_writelane_b32 v254, s11, 29
	s_addc_u32 s11, s9, s5
	s_add_u32 s4, s84, 0x1e800000
	v_writelane_b32 v254, s12, 31
	s_addc_u32 s5, s85, 0
	v_writelane_b32 v254, s4, 33
	s_add_u32 s4, s4, s1
	v_writelane_b32 v254, s5, 35
	s_addc_u32 s5, s5, 0
	s_lshl_b32 s7, s6, 18
	s_add_u32 s76, s4, s7
	s_addc_u32 s77, s5, 0
	s_add_u32 s5, s84, 0x22800000
	s_addc_u32 s12, s85, 0
	s_add_u32 s1, s5, s1
	v_lshrrev_b32_e32 v226, 4, v0
	v_lshlrev_b32_e32 v5, 3, v0
	v_writelane_b32 v254, s5, 37
	s_addc_u32 s5, s12, 0
	v_and_b32_e32 v252, 0x78, v5
	v_lshlrev_b32_e32 v6, 12, v226
	v_mov_b32_e32 v7, v4
	s_add_u32 s78, s1, s7
	v_lshlrev_b32_e32 v2, 1, v252
	v_mov_b32_e32 v3, v4
	v_lshl_add_u64 v[8:9], s[76:77], 0, v[6:7]
	s_addc_u32 s79, s5, 0
	s_lshl_b32 s1, s6, 6
	s_lshl_b32 s5, s6, 8
	s_mov_b32 s9, 0x20000
	v_lshl_add_u64 v[8:9], v[8:9], 0, v[2:3]
	v_readfirstlane_b32 s4, v0
	s_add_u32 s80, s2, s5
	v_add_co_u32_e32 v10, vcc, s9, v8
	v_lshl_add_u64 v[6:7], s[78:79], 0, v[6:7]
	s_addc_u32 s81, s3, 0
	s_lshr_b32 s2, s4, 1
	v_addc_co_u32_e32 v11, vcc, 0, v9, vcc
	global_load_dwordx4 v[114:117], v[8:9], off
	global_load_dwordx4 v[118:121], v[10:11], off
	v_and_b32_e32 v212, 31, v0
	v_lshrrev_b32_e32 v8, 1, v0
	v_lshl_add_u64 v[6:7], v[6:7], 0, v[2:3]
	s_and_b32 s2, s2, 0x7fffffe0
	v_mov_b32_e32 v9, v4
	v_and_b32_e32 v10, 16, v8
	v_add_co_u32_e32 v12, vcc, s9, v6
	v_or_b32_e32 v8, s2, v212
	s_nop 0
	v_addc_co_u32_e32 v13, vcc, 0, v7, vcc
	global_load_dwordx4 v[122:125], v[6:7], off
	global_load_dwordx4 v[126:129], v[12:13], off
	v_lshlrev_b64 v[6:7], 12, v[8:9]
	v_mov_b32_e32 v11, v4
	v_lshl_add_u64 v[6:7], s[10:11], 0, v[6:7]
	v_lshl_add_u64 v[6:7], v[6:7], 0, v[10:11]
	global_load_dwordx4 v[166:169], v[6:7], off
	global_load_dwordx4 v[162:165], v[6:7], off offset:32
	global_load_dwordx4 v[158:161], v[6:7], off offset:64
	global_load_dwordx4 v[146:149], v[6:7], off offset:96
	global_load_dwordx4 v[150:153], v[6:7], off offset:128
	global_load_dwordx4 v[154:157], v[6:7], off offset:160
	global_load_dwordx4 v[174:177], v[6:7], off offset:192
	global_load_dwordx4 v[170:173], v[6:7], off offset:224
	v_and_b32_e32 v3, 0xf0, v0
	v_lshlrev_b32_e32 v9, 8, v226
	v_bitop3_b32 v3, v2, v9, v3 bitop3:0xde
	v_add_u32_e32 v214, 0, v3
	v_lshrrev_b32_e32 v3, 3, v0
	v_lshrrev_b32_e32 v10, 5, v0
	v_bfe_u32 v12, v0, 4, 2
	v_and_b32_e32 v3, 8, v3
	v_and_or_b32 v10, v10, 4, v12
	v_or_b32_e32 v12, 32, v226
	v_and_or_b32 v9, v226, 16, v3
	v_and_or_b32 v3, v12, 48, v3
	v_lshrrev_b32_e32 v9, 1, v9
	v_bfe_u32 v11, v5, 5, 2
	v_lshrrev_b32_e32 v3, 1, v3
	s_sub_i32 s83, s0, s1
	s_lshl_b32 s0, s8, 2
	v_or_b32_e32 v9, v9, v11
	v_or_b32_e32 v3, v3, v11
	s_add_i32 s0, s0, s6
	v_lshlrev_b32_e32 v9, 9, v9
	v_lshlrev_b32_e32 v10, 6, v10
	v_and_b32_e32 v2, 48, v2
	v_lshlrev_b32_e32 v3, 9, v3
	s_sub_i32 s97, 64, s0
	v_or3_b32 v9, v9, v10, v2
	v_or3_b32 v3, v3, v10, v2
	v_lshlrev_b32_e32 v2, 4, v0
	v_lshlrev_b32_e32 v11, 1, v0
	v_lshrrev_b32_e32 v8, 5, v232
	v_and_b32_e32 v10, 0xc0, v2
	v_and_b32_e32 v11, 32, v11
	v_and_b32_e32 v5, 0x118, v5
	s_cmp_lg_u32 0, -1
	v_or3_b32 v5, v11, v10, v5
	v_lshlrev_b32_e32 v10, 8, v212
	v_lshlrev_b32_e32 v11, 4, v8
	v_and_b32_e32 v2, 0xf0, v2
	s_cselect_b32 s0, 0, 0
	v_bitop3_b32 v12, v11, v10, v2 bitop3:0xde
	v_or_b32_e32 v13, 32, v11
	v_or_b32_e32 v14, 64, v11
	v_or_b32_e32 v11, 0x60, v11
	v_add_u32_e32 v215, s0, v5
	v_lshlrev_b32_e32 v5, 11, v226
	v_writelane_b32 v254, s12, 39
	v_bitop3_b32 v13, v13, v10, v2 bitop3:0xde
	v_bitop3_b32 v14, v14, v10, v2 bitop3:0xde
	v_bitop3_b32 v10, v11, v10, v2 bitop3:0xde
	s_waitcnt vmcnt(0)
	v_or_b32_e32 v2, 0x20000, v5
	v_lshlrev_b32_e32 v216, 2, v8
	v_lshlrev_b32_e32 v202, 1, v2
	v_or_b32_e32 v2, 0x30000, v5
	v_writelane_b32 v254, s10, 41
	s_mov_b32 s71, 1
	v_add_u32_e32 v217, -1, v8
	v_cmp_gt_u32_e64 s[0:1], 32, v232
	v_lshlrev_b32_e32 v204, 1, v2
	s_movk_i32 s70, 0x7fff
	s_mov_b32 s96, 0x41000000
	s_mov_b32 s82, 0x3e0293ee
	v_add_u32_e32 v219, 0, v9
	v_add_u32_e32 v220, 0, v3
	v_add_u32_e32 v221, 0, v12
	v_add_u32_e32 v222, 0, v13
	v_add_u32_e32 v223, 0, v14
	v_add_u32_e32 v224, 0, v10
	v_writelane_b32 v254, s11, 42
	s_mov_b64 s[84:85], s[10:11]
	v_sub_u32_e32 v225, v212, v216
	v_mov_b32_e32 v227, 0xff800000
	v_mov_b32_e32 v228, 0xf149f2ca
	s_waitcnt vmcnt(11)
	ds_write_b128 v214, v[114:117] offset:32768
	s_waitcnt vmcnt(10)
	ds_write_b128 v214, v[118:121] offset:40960
	s_waitcnt lgkmcnt(0)
	s_barrier
	s_branch .LBB0_522

; __device__ __forceinline__ unsigned f2bf(float f) { unsigned u = __builtin_bit_cast(unsigned, f); return (u + 0x7fffu + ((u >> 16) & 1u)) >> 16; }
; __device__ __forceinline__ bf16x8 bias_frag(float x, int hi) {
;     const unsigned b1 = f2bf(x); const float r1 = x - __uint_as_float(b1 << 16);
;     const unsigned b2 = f2bf(r1); const float r2 = r1 - __uint_as_float(b2 << 16);
;     const unsigned b3 = f2bf(r2);
;     u32x4 w = {hi ? 0u : (b1 | (b2 << 16)), hi ? 0u : b3, 0u, 0u};
;     return *reinterpret_cast<bf16x8*>(&w);
; }
; template <int KB, int MODE>
; __device__ __forceinline__ void qkt(f32x16& p0, f32x16& p1, const char* K_lds, int r32, int hi, const bf16x8* qr, float bz0, float bz1) {
;     p0 = f32x16{}; p1 = f32x16{};
;     if (MODE == 0) {
;         unsigned hm = (unsigned)hi - 1u; asm volatile("" : "+v"(hm));
;         u32x4 ow = {hm & 0x3f803f80u, hm & 0x00003f80u, 0u, 0u};
;         const bf16x8 ones = *reinterpret_cast<bf16x8*>(&ow);
;         p0 = __builtin_amdgcn_mfma_f32_32x32x16_bf16(bias_frag(bz0, hi), ones, p0, 0, 0, 0);
;         p1 = __builtin_amdgcn_mfma_f32_32x32x16_bf16(bias_frag(bz1, hi), ones, p1, 0, 0, 0);
;     }
;     const char* kb[4];
; #pragma unroll
;     for (int dd = 0; dd < 4; ++dd) kb[dd] = K_lds + KB * SHM_K + KSWZ(r32, (dd * 16 + hi * 8) * 2);
; #pragma unroll
;     for (int d0 = 0; d0 < 8; ++d0) { const char* a = kb[d0 & 3] + (d0 >> 2) * 128;
;         bf16x8 b0 = *reinterpret_cast<const bf16x8*>(a);
;         bf16x8 b1 = *reinterpret_cast<const bf16x8*>(a + 32 * 256);
;         p0 = __builtin_amdgcn_mfma_f32_32x32x16_bf16(b0, qr[d0], p0, 0, 0, 0);
;         p1 = __builtin_amdgcn_mfma_f32_32x32x16_bf16(b1, qr[d0], p1, 0, 0, 0); }
; }
.LBB0_532:
	s_waitcnt vmcnt(1)
	v_bfe_u32 v2, v230, 16, 1
	v_add3_u32 v2, v230, v2, s70
	v_and_b32_e32 v5, 0xffff0000, v2
	v_sub_f32_e32 v5, v230, v5
	v_bfe_u32 v6, v5, 16, 1
	v_add3_u32 v6, v5, v6, s70
	v_and_b32_e32 v6, 0xffff0000, v6
	v_sub_f32_e32 v5, v5, v6
	v_bfe_u32 v7, v5, 16, 1
	s_waitcnt vmcnt(0)
	v_bfe_u32 v22, v229, 16, 1
	v_add3_u32 v5, v5, v7, s70
	v_add3_u32 v26, v229, v22, s70
	v_lshrrev_b32_e32 v5, 16, v5
	v_or_b32_sdwa v2, v6, v2 dst_sel:DWORD dst_unused:UNUSED_PAD src0_sel:DWORD src1_sel:WORD_1
	v_and_b32_e32 v22, 0xffff0000, v26
	v_cndmask_b32_e64 v6, 0, v2, s[0:1]
	v_cndmask_b32_e64 v7, 0, v5, s[0:1]
	v_mov_b32_e32 v8, v4
	v_mov_b32_e32 v9, v4
	v_sub_f32_e32 v27, v229, v22
	v_bfe_u32 v22, v27, 16, 1
	v_mov_b32_e32 v3, v217
	v_add3_u32 v28, v27, v22, s70
	v_and_b32_e32 v28, 0xffff0000, v28
	v_and_b32_e32 v2, 0x3f803f80, v3
	v_and_b32_e32 v3, 0x3f80, v3
	v_mov_b32_e32 v5, v4
	ds_read_b128 v[22:25], v221 offset:32768
	v_xor_b32_e32 v42, 0x80, v221
	ds_read_b128 v[42:45], v42 offset:32768
	v_sub_f32_e32 v27, v27, v28
	v_mfma_f32_32x32x16_bf16 v[6:21], v[6:9], v[2:5], 0
	v_bfe_u32 v29, v27, 16, 1
	v_add3_u32 v27, v27, v29, s70
	v_lshrrev_b32_e32 v27, 16, v27
	v_or_b32_sdwa v26, v28, v26 dst_sel:DWORD dst_unused:UNUSED_PAD src0_sel:DWORD src1_sel:WORD_1
	v_cndmask_b32_e64 v26, 0, v26, s[0:1]
	v_cndmask_b32_e64 v27, 0, v27, s[0:1]
	v_mov_b32_e32 v28, v4
	v_mov_b32_e32 v29, v4
	s_waitcnt lgkmcnt(1)
	v_mfma_f32_32x32x16_bf16 v[6:21], v[22:25], v[166:169], v[6:21]
	ds_read_b128 v[46:49], v221 offset:40960
	v_xor_b32_e32 v50, 0x80, v221
	ds_read_b128 v[50:53], v50 offset:40960
	s_andn2_b64 vcc, exec, s[8:9]
	v_mfma_f32_32x32x16_bf16 v[22:37], v[26:29], v[2:5], 0
	v_cndmask_b32_e64 v2, 0, 1, s[8:9]
	v_cmp_ne_u32_e64 s[6:7], 1, v2
	s_waitcnt lgkmcnt(1)
	v_mfma_f32_32x32x16_bf16 v[22:37], v[46:49], v[166:169], v[22:37]
	ds_read_b128 v[46:49], v222 offset:32768
	v_xor_b32_e32 v54, 0x80, v222
	ds_read_b128 v[54:57], v54 offset:32768
	s_waitcnt lgkmcnt(1)
	v_mfma_f32_32x32x16_bf16 v[6:21], v[46:49], v[162:165], v[6:21]
	ds_read_b128 v[46:49], v222 offset:40960
	v_xor_b32_e32 v58, 0x80, v222
	ds_read_b128 v[58:61], v58 offset:40960
	s_waitcnt lgkmcnt(1)
	v_mfma_f32_32x32x16_bf16 v[22:37], v[46:49], v[162:165], v[22:37]
	ds_read_b128 v[46:49], v223 offset:32768
	v_xor_b32_e32 v62, 0x80, v223
	ds_read_b128 v[62:65], v62 offset:32768
	s_waitcnt lgkmcnt(1)
	v_mfma_f32_32x32x16_bf16 v[6:21], v[46:49], v[158:161], v[6:21]
	ds_read_b128 v[46:49], v223 offset:40960
	v_xor_b32_e32 v66, 0x80, v223
	ds_read_b128 v[66:69], v66 offset:40960
	s_waitcnt lgkmcnt(1)
	v_mfma_f32_32x32x16_bf16 v[22:37], v[46:49], v[158:161], v[22:37]
	ds_read_b128 v[46:49], v224 offset:32768
	v_xor_b32_e32 v70, 0x80, v224
	ds_read_b128 v[70:73], v70 offset:32768
	s_waitcnt lgkmcnt(1)
	v_mfma_f32_32x32x16_bf16 v[6:21], v[46:49], v[146:149], v[6:21]
	ds_read_b128 v[46:49], v224 offset:40960
	v_xor_b32_e32 v74, 0x80, v224
	ds_read_b128 v[74:77], v74 offset:40960
	s_waitcnt lgkmcnt(1)
	v_mfma_f32_32x32x16_bf16 v[22:37], v[46:49], v[146:149], v[22:37]
	v_mfma_f32_32x32x16_bf16 v[6:21], v[42:45], v[150:153], v[6:21]
	v_mfma_f32_32x32x16_bf16 v[22:37], v[50:53], v[150:153], v[22:37]
	v_mfma_f32_32x32x16_bf16 v[6:21], v[54:57], v[154:157], v[6:21]
	v_mfma_f32_32x32x16_bf16 v[22:37], v[58:61], v[154:157], v[22:37]
	v_mfma_f32_32x32x16_bf16 v[6:21], v[62:65], v[174:177], v[6:21]
	v_mfma_f32_32x32x16_bf16 v[22:37], v[66:69], v[174:177], v[22:37]
	v_mfma_f32_32x32x16_bf16 v[6:21], v[70:73], v[170:173], v[6:21]
	s_waitcnt lgkmcnt(0)
	v_mfma_f32_32x32x16_bf16 v[22:37], v[74:77], v[170:173], v[22:37]
	s_cbranch_vccnz .LBB0_534
	v_mov_b32_e32 v41, v4
	v_lshl_add_u64 v[2:3], s[80:81], 0, v[40:41]
	global_load_dword v230, v[2:3], off offset:256
	global_load_dword v229, v[2:3], off offset:384

; __device__ __forceinline__ void finishSM(f32x16& p0, f32x16& p1, float alpha, float& l_reg, bf16x8& pa0, bf16x8& pa1, bf16x8& pa2, bf16x8& pa3) {
; #pragma unroll
;     for (int r = 0; r < 16; ++r) p1[r] = __builtin_amdgcn_exp2f(p1[r]);
;     float ps = 0;
; #pragma unroll
;     for (int r = 0; r < 16; ++r) ps += p0[r];
; #pragma unroll
;     for (int r = 0; r < 16; ++r) ps += p1[r];
;     { auto rr = __builtin_amdgcn_permlane32_swap(__float_as_uint(ps), __float_as_uint(ps), false, false);
;       ps = __uint_as_float(rr[0]) + __uint_as_float(rr[1]); }
;     l_reg = l_reg * alpha + ps;
;     ...
;     PK4(p0, 0, pa0); PK4(p0, 8, pa1); PK4(p1, 0, pa2); PK4(p1, 8, pa3);
; template <int KB, int MODE>
; __device__ __forceinline__ void qkt(f32x16& p0, f32x16& p1, const char* K_lds, int r32, int hi, const bf16x8* qr, float bz0, float bz1) {
;     p0 = f32x16{}; p1 = f32x16{};
;     if (MODE == 0) {
;         unsigned hm = (unsigned)hi - 1u; asm volatile("" : "+v"(hm));
;         u32x4 ow = {hm & 0x3f803f80u, hm & 0x00003f80u, 0u, 0u};
;         const bf16x8 ones = *reinterpret_cast<bf16x8*>(&ow);
;         p0 = __builtin_amdgcn_mfma_f32_32x32x16_bf16(bias_frag(bz0, hi), ones, p0, 0, 0, 0);
;         p1 = __builtin_amdgcn_mfma_f32_32x32x16_bf16(bias_frag(bz1, hi), ones, p1, 0, 0, 0);
;     }
;     const char* kb[4];
; #pragma unroll
;     for (int dd = 0; dd < 4; ++dd) kb[dd] = K_lds + KB * SHM_K + KSWZ(r32, (dd * 16 + hi * 8) * 2);
; #pragma unroll
;     for (int d0 = 0; d0 < 8; ++d0) { const char* a = kb[d0 & 3] + (d0 >> 2) * 128;
;         bf16x8 b0 = *reinterpret_cast<const bf16x8*>(a);
;         bf16x8 b1 = *reinterpret_cast<const bf16x8*>(a + 32 * 256);
;         p0 = __builtin_amdgcn_mfma_f32_32x32x16_bf16(b0, qr[d0], p0, 0, 0, 0);
;         p1 = __builtin_amdgcn_mfma_f32_32x32x16_bf16(b1, qr[d0], p1, 0, 0, 0); }
; }
.LBB0_542:
	s_waitcnt vmcnt(1)
	v_bfe_u32 v2, v230, 16, 1
	v_add3_u32 v2, v230, v2, s70
	v_and_b32_e32 v5, 0xffff0000, v2
	v_sub_f32_e32 v5, v230, v5
	v_bfe_u32 v6, v5, 16, 1
	v_add3_u32 v6, v5, v6, s70
	v_and_b32_e32 v6, 0xffff0000, v6
	v_sub_f32_e32 v5, v5, v6
	v_bfe_u32 v7, v5, 16, 1
	v_add3_u32 v5, v5, v7, s70
	v_lshrrev_b32_e32 v5, 16, v5
	v_or_b32_sdwa v2, v6, v2 dst_sel:DWORD dst_unused:UNUSED_PAD src0_sel:DWORD src1_sel:WORD_1
	v_cndmask_b32_e64 v6, 0, v2, s[0:1]
	v_cndmask_b32_e64 v7, 0, v5, s[0:1]
	v_mov_b32_e32 v8, v4
	v_mov_b32_e32 v9, v4
	v_mov_b32_e32 v3, v217
	v_mov_b32_e32 v5, v4
	v_and_b32_e32 v2, 0x3f803f80, v3
	v_and_b32_e32 v3, 0x3f80, v3
	v_exp_f32_e32 v140, v140
	v_exp_f32_e32 v141, v141
	v_mfma_f32_32x32x16_bf16 v[102:117], v[6:9], v[2:5], 0
	s_waitcnt vmcnt(0)
	v_bfe_u32 v6, v229, 16, 1
	v_add3_u32 v6, v229, v6, s70
	v_and_b32_e32 v7, 0xffff0000, v6
	v_sub_f32_e32 v7, v229, v7
	v_bfe_u32 v8, v7, 16, 1
	v_add3_u32 v8, v7, v8, s70
	v_and_b32_e32 v8, 0xffff0000, v8
	v_sub_f32_e32 v7, v7, v8
	v_bfe_u32 v9, v7, 16, 1
	v_add3_u32 v7, v7, v9, s70
	v_lshrrev_b32_e32 v7, 16, v7
	v_or_b32_sdwa v6, v8, v6 dst_sel:DWORD dst_unused:UNUSED_PAD src0_sel:DWORD src1_sel:WORD_1
	v_cndmask_b32_e64 v6, 0, v6, s[0:1]
	v_cndmask_b32_e64 v7, 0, v7, s[0:1]
	v_mov_b32_e32 v8, v4
	v_mov_b32_e32 v9, v4
	v_exp_f32_e32 v138, v138
	v_exp_f32_e32 v139, v139
	v_mfma_f32_32x32x16_bf16 v[86:101], v[6:9], v[2:5], 0
	ds_read_b128 v[6:9], v221 offset:49152
	v_xor_b32_e32 v10, 0x80, v221
	ds_read_b128 v[10:13], v10 offset:49152
	v_exp_f32_e32 v2, v144
	v_exp_f32_e32 v3, v145
	v_exp_f32_e32 v5, v142
	v_exp_f32_e32 v142, v143
	v_exp_f32_e32 v136, v136
	v_exp_f32_e32 v137, v137
	s_waitcnt lgkmcnt(1)
	v_mfma_f32_32x32x16_bf16 v[102:117], v[6:9], v[166:169], v[102:117]
	ds_read_b128 v[6:9], v221 offset:57344
	v_xor_b32_e32 v14, 0x80, v221
	ds_read_b128 v[14:17], v14 offset:57344
	v_exp_f32_e32 v134, v134
	v_exp_f32_e32 v135, v135
	v_exp_f32_e32 v132, v132
	s_waitcnt lgkmcnt(1)
	v_mfma_f32_32x32x16_bf16 v[86:101], v[6:9], v[166:169], v[86:101]
	ds_read_b128 v[6:9], v222 offset:49152
	v_xor_b32_e32 v82, 0x80, v222
	ds_read_b128 v[82:85], v82 offset:49152
	s_waitcnt lgkmcnt(1)
	v_mfma_f32_32x32x16_bf16 v[102:117], v[6:9], v[162:165], v[102:117]
	ds_read_b128 v[6:9], v222 offset:57344
	v_xor_b32_e32 v118, 0x80, v222
	ds_read_b128 v[118:121], v118 offset:57344
	s_waitcnt lgkmcnt(1)
	v_mfma_f32_32x32x16_bf16 v[86:101], v[6:9], v[162:165], v[86:101]
	ds_read_b128 v[6:9], v223 offset:49152
	v_xor_b32_e32 v122, 0x80, v223
	ds_read_b128 v[122:125], v122 offset:49152
	s_waitcnt lgkmcnt(1)
	v_mfma_f32_32x32x16_bf16 v[102:117], v[6:9], v[158:161], v[102:117]
	ds_read_b128 v[6:9], v223 offset:57344
	v_xor_b32_e32 v126, 0x80, v223
	ds_read_b128 v[126:129], v126 offset:57344
	ds_read_b128 v[236:239], v224 offset:49152
	v_xor_b32_e32 v240, 0x80, v224
	ds_read_b128 v[240:243], v240 offset:49152
	s_waitcnt lgkmcnt(3)
	v_mfma_f32_32x32x16_bf16 v[86:101], v[6:9], v[158:161], v[86:101]
	ds_read_b128 v[6:9], v224 offset:57344
	v_xor_b32_e32 v244, 0x80, v224
	ds_read_b128 v[244:247], v244 offset:57344
	s_waitcnt lgkmcnt(3)
	v_mfma_f32_32x32x16_bf16 v[102:117], v[236:239], v[146:149], v[102:117]
	s_waitcnt lgkmcnt(1)
	v_mfma_f32_32x32x16_bf16 v[86:101], v[6:9], v[146:149], v[86:101]
	v_add_f32_e32 v9, 0, v193
	v_add_f32_e32 v9, v195, v9
	v_add_f32_e32 v9, v191, v9
	v_add_f32_e32 v9, v194, v9
	v_add_f32_e32 v9, v189, v9
	v_add_f32_e32 v9, v192, v9
	v_add_f32_e32 v9, v188, v9
	v_mfma_f32_32x32x16_bf16 v[102:117], v[10:13], v[150:153], v[102:117]
	v_add_f32_e32 v9, v190, v9
	v_add_f32_e32 v9, v181, v9
	v_add_f32_e32 v9, v185, v9
	v_add_f32_e32 v9, v180, v9
	v_add_f32_e32 v9, v183, v9
	v_add_f32_e32 v9, v179, v9
	v_add_f32_e32 v9, v187, v9
	v_mfma_f32_32x32x16_bf16 v[86:101], v[14:17], v[150:153], v[86:101]
	v_add_f32_e32 v9, v184, v9
	v_add_f32_e32 v9, v186, v9
	v_add_f32_e32 v9, v2, v9
	v_add_f32_e32 v9, v3, v9
	v_add_f32_e32 v9, v5, v9
	v_add_f32_e32 v9, v142, v9
	v_add_f32_e32 v9, v140, v9
	v_mfma_f32_32x32x16_bf16 v[102:117], v[82:85], v[154:157], v[102:117]
	v_add_f32_e32 v9, v141, v9
	v_add_f32_e32 v9, v138, v9
	v_add_f32_e32 v9, v139, v9
	v_add_f32_e32 v9, v136, v9
	v_exp_f32_e32 v6, v133
	v_add_f32_e32 v9, v137, v9
	v_exp_f32_e32 v7, v130
	v_mfma_f32_32x32x16_bf16 v[86:101], v[118:121], v[154:157], v[86:101]
	v_add_f32_e32 v9, v134, v9
	v_exp_f32_e32 v8, v131
	v_add_f32_e32 v9, v135, v9
	v_add_f32_e32 v9, v132, v9
	v_add_f32_e32 v9, v6, v9
	v_add_f32_e32 v9, v7, v9
	v_add_f32_e32 v235, v8, v9
	v_mfma_f32_32x32x16_bf16 v[102:117], v[122:125], v[174:177], v[102:117]
	v_mov_b32_e32 v236, v235
	s_nop 1
	v_permlane32_swap_b32_e32 v235, v236
	v_cvt_pk_bf16_f32 v82, v193, v195
	v_cvt_pk_bf16_f32 v83, v191, v194
	v_cvt_pk_bf16_f32 v84, v189, v192
	v_cvt_pk_bf16_f32 v85, v188, v190
	v_mfma_f32_32x32x16_bf16 v[86:101], v[126:129], v[174:177], v[86:101]
	v_cvt_pk_bf16_f32 v118, v181, v185
	v_cvt_pk_bf16_f32 v119, v180, v183
	v_cvt_pk_bf16_f32 v120, v179, v187
	v_cvt_pk_bf16_f32 v121, v184, v186
	v_cvt_pk_bf16_f32 v122, v2, v3
	v_cvt_pk_bf16_f32 v123, v5, v142
	v_cvt_pk_bf16_f32 v124, v140, v141
	v_mfma_f32_32x32x16_bf16 v[102:117], v[240:243], v[170:173], v[102:117]
	v_cvt_pk_bf16_f32 v125, v138, v139
	v_cvt_pk_bf16_f32 v126, v136, v137
	v_cvt_pk_bf16_f32 v127, v134, v135
	v_cvt_pk_bf16_f32 v128, v132, v6
	v_cvt_pk_bf16_f32 v129, v7, v8
	v_permlane32_swap_b32_e32 v82, v84
	s_waitcnt lgkmcnt(0)
; __device__ __forceinline__ void finishSM(f32x16& p0, f32x16& p1, float alpha, float& l_reg, bf16x8& pa0, bf16x8& pa1, bf16x8& pa2, bf16x8& pa3) {
;     ...
;     PK4(p0, 0, pa0); PK4(p0, 8, pa1); PK4(p1, 0, pa2); PK4(p1, 8, pa3);
; template <int VB>
; __device__ __forceinline__ void pv_tile(f32x16* o, int vb0, bf16x8 pa0, bf16x8 pa1, bf16x8 pa2, bf16x8 pa3) {
;     ...
;     PV_D0(0); PV_D0(1); PV_D0(2); PV_D0(3);
	v_mfma_f32_32x32x16_bf16 v[86:101], v[244:247], v[170:173], v[86:101]
	v_permlane32_swap_b32_e32 v83, v85
	v_permlane32_swap_b32_e32 v118, v120
	v_permlane32_swap_b32_e32 v119, v121
	v_permlane32_swap_b32_e32 v122, v124
	v_permlane32_swap_b32_e32 v123, v125
	v_permlane32_swap_b32_e32 v126, v128
	v_permlane32_swap_b32_e32 v127, v129
	v_add_u32_e32 v239, s72, v226
	v_add_u32_e32 v2, 1, v239
	v_mov_b32_e32 v3, v4
	v_add_u32_e32 v8, 33, v239
	v_mov_b32_e32 v9, v4
	v_lshlrev_b64 v[2:3], 12, v[2:3]
	v_lshlrev_b64 v[14:15], 12, v[8:9]
	v_lshl_add_u64 v[6:7], v[206:207], 0, v[2:3]
	v_lshl_add_u64 v[10:11], v[206:207], 0, v[14:15]
	v_lshl_add_u64 v[2:3], v[208:209], 0, v[2:3]
	v_add_u32_e32 v240, s72, v212
	global_load_dwordx4 v[6:9], v[6:7], off
	s_nop 0
	global_load_dwordx4 v[10:13], v[10:11], off
	v_lshl_add_u64 v[130:131], v[208:209], 0, v[14:15]
	global_load_dwordx4 v[14:17], v[2:3], off
	global_load_dwordx4 v[178:181], v[130:131], off
	v_add_u32_e32 v2, 1, v240
	v_mov_b32_e32 v3, v4
	v_lshl_add_u64 v[2:3], v[2:3], 2, s[80:81]
	global_load_dword v230, v[2:3], off
	global_load_dword v229, v[2:3], off offset:128
	ds_read_b64_tr_b16 v[130:131], v215 offset:0
	ds_read_b64_tr_b16 v[132:133], v215 offset:0x800
	ds_read_b64_tr_b16 v[134:135], v215 offset:0x1000
	ds_read_b64_tr_b16 v[136:137], v215 offset:0x1800
	ds_read_b64_tr_b16 v[138:139], v215 offset:0x2000
	ds_read_b64_tr_b16 v[140:141], v215 offset:0x2800
	ds_read_b64_tr_b16 v[142:143], v215 offset:0x3000
	ds_read_b64_tr_b16 v[144:145], v215 offset:0x3800
	s_waitcnt lgkmcnt(0)
	s_nop 0
	v_mfma_f32_32x32x16_bf16 v[66:81], v[82:85], v[130:133], v[66:81]
	ds_read_b64_tr_b16 v[130:131], v215 offset:0x200
	ds_read_b64_tr_b16 v[132:133], v215 offset:0xa00
	v_mfma_f32_32x32x16_bf16 v[66:81], v[118:121], v[134:137], v[66:81]
	ds_read_b64_tr_b16 v[134:135], v215 offset:0x1200
	ds_read_b64_tr_b16 v[136:137], v215 offset:0x1a00
	v_mfma_f32_32x32x16_bf16 v[66:81], v[122:125], v[138:141], v[66:81]
	ds_read_b64_tr_b16 v[138:139], v215 offset:0x2200
	ds_read_b64_tr_b16 v[140:141], v215 offset:0x2a00
	ds_read_b64_tr_b16 v[184:185], v215 offset:0x3200
	ds_read_b64_tr_b16 v[186:187], v215 offset:0x3a00
	s_waitcnt lgkmcnt(0)
	v_mfma_f32_32x32x16_bf16 v[66:81], v[126:129], v[142:145], v[66:81]
	v_mfma_f32_32x32x16_bf16 v[50:65], v[82:85], v[130:133], v[50:65]
	ds_read_b64_tr_b16 v[130:131], v215 offset:0x400
	ds_read_b64_tr_b16 v[132:133], v215 offset:0xc00
	v_mfma_f32_32x32x16_bf16 v[50:65], v[118:121], v[134:137], v[50:65]
	ds_read_b64_tr_b16 v[134:135], v215 offset:0x1400
	ds_read_b64_tr_b16 v[136:137], v215 offset:0x1c00
	v_mfma_f32_32x32x16_bf16 v[50:65], v[122:125], v[138:141], v[50:65]
	ds_read_b64_tr_b16 v[138:139], v215 offset:0x2400
	ds_read_b64_tr_b16 v[140:141], v215 offset:0x2c00
	ds_read_b64_tr_b16 v[142:143], v215 offset:0x3400
	ds_read_b64_tr_b16 v[144:145], v215 offset:0x3c00
	s_waitcnt lgkmcnt(0)
	v_mfma_f32_32x32x16_bf16 v[50:65], v[126:129], v[184:187], v[50:65]
	v_mfma_f32_32x32x16_bf16 v[34:49], v[82:85], v[130:133], v[34:49]
	ds_read_b64_tr_b16 v[130:131], v215 offset:0x600
	ds_read_b64_tr_b16 v[132:133], v215 offset:0xe00
	v_mfma_f32_32x32x16_bf16 v[34:49], v[118:121], v[134:137], v[34:49]
	ds_read_b64_tr_b16 v[134:135], v215 offset:0x1600
	ds_read_b64_tr_b16 v[136:137], v215 offset:0x1e00
	v_mfma_f32_32x32x16_bf16 v[34:49], v[122:125], v[138:141], v[34:49]
	ds_read_b64_tr_b16 v[138:139], v215 offset:0x2600
	ds_read_b64_tr_b16 v[140:141], v215 offset:0x2e00
	ds_read_b64_tr_b16 v[184:185], v215 offset:0x3600
	ds_read_b64_tr_b16 v[186:187], v215 offset:0x3e00
	s_waitcnt lgkmcnt(0)
	v_mfma_f32_32x32x16_bf16 v[34:49], v[126:129], v[142:145], v[34:49]
	v_mfma_f32_32x32x16_bf16 v[18:33], v[82:85], v[130:133], v[18:33]
	s_cmp_le_i32 s72, s74
	v_mfma_f32_32x32x16_bf16 v[18:33], v[118:121], v[134:137], v[18:33]
	v_mfma_f32_32x32x16_bf16 v[18:33], v[122:125], v[138:141], v[18:33]
	v_mfma_f32_32x32x16_bf16 v[18:33], v[126:129], v[184:187], v[18:33]
	s_cbranch_scc1 .LBB0_544
; __device__ __forceinline__ void mask_causal(f32x16& p0, f32x16& p1, int dq) {
;     const float NEG = -__builtin_inff();
; #pragma unroll
;     for (int r = 0; r < 16; ++r) {
;         const int c = (r & 3) + 8 * (r >> 2);
;         if (dq - c < 0) p0[r] = NEG;
;         if (dq - c - 32 < 0) p1[r] = NEG;
;     }
; }
	v_add_u32_e32 v2, 64, v234
	v_cmp_gt_i32_e64 s[64:65], 26, v2
	v_cmp_gt_i32_e64 s[66:67], 27, v2
	v_cmp_gt_i32_e64 s[62:63], 25, v2
	s_and_b64 s[64:65], s[66:67], s[64:65]
	v_cmp_gt_i32_e64 s[60:61], 24, v2
	s_and_b64 s[62:63], s[64:65], s[62:63]
	v_cmp_gt_i32_e64 s[58:59], 19, v2
	s_and_b64 s[60:61], s[62:63], s[60:61]
	v_cmp_gt_i32_e64 s[56:57], 18, v2
	s_and_b64 s[58:59], s[60:61], s[58:59]
	v_cmp_gt_i32_e64 s[54:55], 17, v2
	s_and_b64 s[56:57], s[58:59], s[56:57]
	v_cmp_gt_i32_e64 s[52:53], 16, v2
	s_and_b64 s[54:55], s[56:57], s[54:55]
	v_cmp_gt_i32_e64 s[50:51], 11, v2
	s_and_b64 s[52:53], s[54:55], s[52:53]
	v_cmp_gt_i32_e64 s[48:49], 10, v2
	s_and_b64 s[50:51], s[52:53], s[50:51]
	v_cmp_gt_i32_e64 s[46:47], 9, v2
	s_and_b64 s[48:49], s[50:51], s[48:49]
	v_cmp_gt_i32_e64 s[44:45], 8, v2
	s_and_b64 s[46:47], s[48:49], s[46:47]
	v_cmp_gt_i32_e64 s[42:43], 3, v2
	s_and_b64 s[44:45], s[46:47], s[44:45]
	v_cmp_gt_i32_e64 s[40:41], 2, v2
	s_and_b64 s[42:43], s[44:45], s[42:43]
	v_cmp_gt_i32_e64 s[38:39], 1, v2
	s_and_b64 s[40:41], s[42:43], s[40:41]
	v_cmp_gt_i32_e64 s[36:37], 0, v2
	s_and_b64 s[38:39], s[40:41], s[38:39]
	s_and_b64 s[36:37], s[38:39], s[36:37]
	v_cmp_gt_i32_e64 s[34:35], 58, v2
	v_cndmask_b32_e64 v102, v102, v227, s[36:37]
	v_cmp_gt_i32_e64 s[36:37], 59, v2
	v_cmp_gt_i32_e64 s[30:31], 57, v2
	s_and_b64 s[34:35], s[36:37], s[34:35]
	v_cmp_gt_i32_e64 s[28:29], 56, v2
	s_and_b64 s[30:31], s[34:35], s[30:31]
	v_cmp_gt_i32_e64 s[26:27], 51, v2
	s_and_b64 s[28:29], s[30:31], s[28:29]
	v_cmp_gt_i32_e64 s[24:25], 50, v2
	s_and_b64 s[26:27], s[28:29], s[26:27]
	v_cmp_gt_i32_e64 s[22:23], 49, v2
	s_and_b64 s[24:25], s[26:27], s[24:25]
	v_cmp_gt_i32_e64 s[20:21], 48, v2
	s_and_b64 s[22:23], s[24:25], s[22:23]
	v_cmp_gt_i32_e64 s[18:19], 43, v2
	s_and_b64 s[20:21], s[22:23], s[20:21]
	v_cmp_gt_i32_e64 s[16:17], 42, v2
	s_and_b64 s[18:19], s[20:21], s[18:19]
	v_cmp_gt_i32_e64 s[14:15], 41, v2
	s_and_b64 s[16:17], s[18:19], s[16:17]
	v_cmp_gt_i32_e64 s[12:13], 40, v2
	s_and_b64 s[14:15], s[16:17], s[14:15]
	v_cmp_gt_i32_e64 s[10:11], 35, v2
	s_and_b64 s[12:13], s[14:15], s[12:13]
	v_cmp_gt_i32_e64 s[8:9], 34, v2
	s_and_b64 s[10:11], s[12:13], s[10:11]
	v_cmp_gt_i32_e64 s[6:7], 33, v2
	s_and_b64 s[8:9], s[10:11], s[8:9]
	v_cmp_gt_i32_e32 vcc, 32, v2
	s_and_b64 s[6:7], s[8:9], s[6:7]
	s_and_b64 vcc, s[6:7], vcc
	v_cndmask_b32_e64 v117, v117, v227, s[66:67]
	v_cndmask_b32_e64 v116, v116, v227, s[64:65]
	v_cndmask_b32_e64 v115, v115, v227, s[62:63]
	v_cndmask_b32_e64 v114, v114, v227, s[60:61]
	v_cndmask_b32_e64 v113, v113, v227, s[58:59]
	v_cndmask_b32_e64 v112, v112, v227, s[56:57]
	v_cndmask_b32_e64 v111, v111, v227, s[54:55]
	v_cndmask_b32_e64 v110, v110, v227, s[52:53]
	v_cndmask_b32_e64 v109, v109, v227, s[50:51]
	v_cndmask_b32_e64 v108, v108, v227, s[48:49]
	v_cndmask_b32_e64 v107, v107, v227, s[46:47]
	v_cndmask_b32_e64 v106, v106, v227, s[44:45]
	v_cndmask_b32_e64 v105, v105, v227, s[42:43]
	v_cndmask_b32_e64 v104, v104, v227, s[40:41]
	v_cndmask_b32_e64 v103, v103, v227, s[38:39]
	v_cndmask_b32_e64 v101, v101, v227, s[36:37]
	v_cndmask_b32_e64 v100, v100, v227, s[34:35]
	v_cndmask_b32_e64 v99, v99, v227, s[30:31]
	v_cndmask_b32_e64 v98, v98, v227, s[28:29]
	v_cndmask_b32_e64 v97, v97, v227, s[26:27]
	v_cndmask_b32_e64 v96, v96, v227, s[24:25]
	v_cndmask_b32_e64 v95, v95, v227, s[22:23]
	v_cndmask_b32_e64 v94, v94, v227, s[20:21]
	v_cndmask_b32_e64 v93, v93, v227, s[18:19]
	v_cndmask_b32_e64 v92, v92, v227, s[16:17]
	v_cndmask_b32_e64 v91, v91, v227, s[14:15]
	v_cndmask_b32_e64 v90, v90, v227, s[12:13]
	v_cndmask_b32_e64 v89, v89, v227, s[10:11]
	v_cndmask_b32_e64 v88, v88, v227, s[8:9]
	v_cndmask_b32_e64 v87, v87, v227, s[6:7]
	v_cndmask_b32_e32 v86, v86, v227, vcc

; __device__ __forceinline__ void partialSM(f32x16& p0, f32x16& p1, float& m_reg, float& mn, float& alpha) {
;     ...
;     constexpr float C2 = 1.4426950408889634f * SM_SCALE;
;     if (__builtin_expect(__all((pmax - m_reg) * SM_SCALE <= THR), 1)) { mn = m_reg; alpha = 1.f; }
;     else { mn = fmaxf(m_reg, pmax); alpha = __builtin_amdgcn_exp2f((m_reg - mn) * C2); m_reg = mn; }
;     const float mnL = -mn * C2;
; #pragma unroll
;     for (int r = 0; r < 16; ++r) p0[r] = fmaf(p0[r], C2, mnL);
; #pragma unroll
;     for (int r = 0; r < 16; ++r) p1[r] = fmaf(p1[r], C2, mnL);
; #pragma unroll
;     for (int r = 0; r < 16; ++r) p0[r] = __builtin_amdgcn_exp2f(p0[r]);
.LBB0_548:
	v_cndmask_b32_e64 v238, v2, v182, s[6:7]
	v_mul_f32_e32 v182, 0xbe0293ee, v238
	v_fmamk_f32 v2, v102, 0x3e0293ee, v182
	v_fmamk_f32 v3, v103, 0x3e0293ee, v182
	v_fmamk_f32 v5, v104, 0x3e0293ee, v182
	v_fmamk_f32 v85, v105, 0x3e0293ee, v182
	v_fmamk_f32 v118, v106, 0x3e0293ee, v182
	v_fmamk_f32 v119, v107, 0x3e0293ee, v182
	v_fmamk_f32 v120, v108, 0x3e0293ee, v182
	v_fmamk_f32 v121, v109, 0x3e0293ee, v182
	v_fmamk_f32 v122, v110, 0x3e0293ee, v182
	v_fmamk_f32 v123, v111, 0x3e0293ee, v182
	v_fmamk_f32 v124, v112, 0x3e0293ee, v182
	v_fmamk_f32 v125, v113, 0x3e0293ee, v182
	v_fmamk_f32 v114, v114, 0x3e0293ee, v182
	v_fmamk_f32 v115, v115, 0x3e0293ee, v182
	v_fmamk_f32 v116, v116, 0x3e0293ee, v182
	v_fmamk_f32 v117, v117, 0x3e0293ee, v182
	v_fmamk_f32 v102, v86, 0x3e0293ee, v182
	v_fmamk_f32 v103, v87, 0x3e0293ee, v182
	v_fmamk_f32 v111, v88, 0x3e0293ee, v182
	v_fmamk_f32 v112, v89, 0x3e0293ee, v182
	v_fmamk_f32 v113, v90, 0x3e0293ee, v182
	v_fmamk_f32 v183, v91, 0x3e0293ee, v182
	v_fmamk_f32 v104, v92, 0x3e0293ee, v182
	v_fmamk_f32 v105, v93, 0x3e0293ee, v182
	v_fmamk_f32 v106, v94, 0x3e0293ee, v182
	v_fmamk_f32 v107, v95, 0x3e0293ee, v182
	v_fmamk_f32 v108, v96, 0x3e0293ee, v182
	v_fmamk_f32 v109, v97, 0x3e0293ee, v182
	v_exp_f32_e32 v82, v2
	v_exp_f32_e32 v83, v3
	v_exp_f32_e32 v84, v5
	v_exp_f32_e32 v85, v85
	v_exp_f32_e32 v86, v118
	v_exp_f32_e32 v87, v119
	v_exp_f32_e32 v88, v120
	v_exp_f32_e32 v89, v121
	v_exp_f32_e32 v90, v122
	v_exp_f32_e32 v91, v123
	v_exp_f32_e32 v92, v124
	v_exp_f32_e32 v93, v125
	v_exp_f32_e32 v94, v114
	v_exp_f32_e32 v95, v115
	v_exp_f32_e32 v96, v116
	v_exp_f32_e32 v97, v117
	v_fmamk_f32 v110, v98, 0x3e0293ee, v182
	v_fmamk_f32 v184, v99, 0x3e0293ee, v182
	v_fmamk_f32 v185, v100, 0x3e0293ee, v182
	v_fmac_f32_e32 v182, 0x3e0293ee, v101
	s_waitcnt lgkmcnt(0)
	s_barrier
; __device__ __forceinline__ void finishSM(f32x16& p0, f32x16& p1, float alpha, float& l_reg, bf16x8& pa0, bf16x8& pa1, bf16x8& pa2, bf16x8& pa3) {
; #pragma unroll
;     for (int r = 0; r < 16; ++r) p1[r] = __builtin_amdgcn_exp2f(p1[r]);
;     float ps = 0;
; #pragma unroll
;     for (int r = 0; r < 16; ++r) ps += p0[r];
; #pragma unroll
;     for (int r = 0; r < 16; ++r) ps += p1[r];
;     { auto rr = __builtin_amdgcn_permlane32_swap(__float_as_uint(ps), __float_as_uint(ps), false, false);
;       ps = __uint_as_float(rr[0]) + __uint_as_float(rr[1]); }
;     l_reg = l_reg * alpha + ps;
;     ...
;     PK4(p0, 0, pa0); PK4(p0, 8, pa1); PK4(p1, 0, pa2); PK4(p1, 8, pa3);
; template <int KB, int MODE>
; __device__ __forceinline__ void qkt(f32x16& p0, f32x16& p1, const char* K_lds, int r32, int hi, const bf16x8* qr, float bz0, float bz1) {
;     p0 = f32x16{}; p1 = f32x16{};
;     if (MODE == 0) {
;         unsigned hm = (unsigned)hi - 1u; asm volatile("" : "+v"(hm));
;         u32x4 ow = {hm & 0x3f803f80u, hm & 0x00003f80u, 0u, 0u};
;         const bf16x8 ones = *reinterpret_cast<bf16x8*>(&ow);
;         p0 = __builtin_amdgcn_mfma_f32_32x32x16_bf16(bias_frag(bz0, hi), ones, p0, 0, 0, 0);
;         p1 = __builtin_amdgcn_mfma_f32_32x32x16_bf16(bias_frag(bz1, hi), ones, p1, 0, 0, 0);
;     }
;     const char* kb[4];
; #pragma unroll
;     for (int dd = 0; dd < 4; ++dd) kb[dd] = K_lds + KB * SHM_K + KSWZ(r32, (dd * 16 + hi * 8) * 2);
; #pragma unroll
;     for (int d0 = 0; d0 < 8; ++d0) { const char* a = kb[d0 & 3] + (d0 >> 2) * 128;
;         bf16x8 b0 = *reinterpret_cast<const bf16x8*>(a);
;         bf16x8 b1 = *reinterpret_cast<const bf16x8*>(a + 32 * 256);
;         p0 = __builtin_amdgcn_mfma_f32_32x32x16_bf16(b0, qr[d0], p0, 0, 0, 0);
;         p1 = __builtin_amdgcn_mfma_f32_32x32x16_bf16(b1, qr[d0], p1, 0, 0, 0); }
; }
	s_waitcnt vmcnt(1)
	v_bfe_u32 v98, v230, 16, 1
	v_add3_u32 v98, v230, v98, s70
	v_and_b32_e32 v99, 0xffff0000, v98
	v_sub_f32_e32 v99, v230, v99
	v_bfe_u32 v100, v99, 16, 1
	v_add3_u32 v100, v99, v100, s70
	v_and_b32_e32 v100, 0xffff0000, v100
	v_sub_f32_e32 v99, v99, v100
	v_bfe_u32 v101, v99, 16, 1
	v_add3_u32 v99, v99, v101, s70
	v_lshrrev_b32_e32 v99, 16, v99
	v_or_b32_sdwa v98, v100, v98 dst_sel:DWORD dst_unused:UNUSED_PAD src0_sel:DWORD src1_sel:WORD_1
	v_cndmask_b32_e64 v98, 0, v98, s[0:1]
	v_cndmask_b32_e64 v99, 0, v99, s[0:1]
	v_mov_b32_e32 v100, v4
	v_mov_b32_e32 v101, v4
	v_mov_b32_e32 v3, v217
	v_mov_b32_e32 v5, v4
	v_and_b32_e32 v2, 0x3f803f80, v3
	v_and_b32_e32 v3, 0x3f80, v3
	v_exp_f32_e32 v104, v104
	v_exp_f32_e32 v105, v105
	v_mfma_f32_32x32x16_bf16 v[130:145], v[98:101], v[2:5], 0
	s_waitcnt vmcnt(0)
	v_bfe_u32 v98, v229, 16, 1
	v_add3_u32 v98, v229, v98, s70
	v_and_b32_e32 v99, 0xffff0000, v98
	v_sub_f32_e32 v99, v229, v99
	v_bfe_u32 v100, v99, 16, 1
	v_add3_u32 v100, v99, v100, s70
	v_and_b32_e32 v100, 0xffff0000, v100
	v_sub_f32_e32 v99, v99, v100
	v_bfe_u32 v101, v99, 16, 1
	v_add3_u32 v99, v99, v101, s70
	v_lshrrev_b32_e32 v99, 16, v99
	v_or_b32_sdwa v98, v100, v98 dst_sel:DWORD dst_unused:UNUSED_PAD src0_sel:DWORD src1_sel:WORD_1
	v_cndmask_b32_e64 v98, 0, v98, s[0:1]
	v_cndmask_b32_e64 v99, 0, v99, s[0:1]
	v_mov_b32_e32 v100, v4
	v_mov_b32_e32 v101, v4
	v_exp_f32_e32 v106, v106
	v_exp_f32_e32 v107, v107
	v_mfma_f32_32x32x16_bf16 v[114:129], v[98:101], v[2:5], 0
	ds_read_b128 v[98:101], v221 offset:32768
	ds_read_b128 v[186:189], v221 offset:40960
	v_add_f32_e32 v2, 0, v82
	v_add_f32_e32 v2, v83, v2
	v_add_f32_e32 v2, v84, v2
	v_add_f32_e32 v2, v85, v2
	v_add_f32_e32 v2, v86, v2
	v_add_f32_e32 v2, v87, v2
	s_waitcnt lgkmcnt(1)
	v_mfma_f32_32x32x16_bf16 v[130:145], v[98:101], v[166:169], v[130:145]
	v_add_f32_e32 v2, v88, v2
	v_add_f32_e32 v2, v89, v2
	v_add_f32_e32 v2, v90, v2
	v_add_f32_e32 v2, v91, v2
	v_add_f32_e32 v2, v92, v2
	v_add_f32_e32 v2, v93, v2
	v_add_f32_e32 v2, v94, v2
	s_waitcnt lgkmcnt(0)
	v_mfma_f32_32x32x16_bf16 v[114:129], v[186:189], v[166:169], v[114:129]
	ds_read_b128 v[98:101], v222 offset:32768
	ds_read_b128 v[186:189], v222 offset:40960
	v_add_f32_e32 v2, v95, v2
	v_add_f32_e32 v2, v96, v2
	v_add_f32_e32 v2, v97, v2
	v_exp_f32_e32 v108, v108
	v_exp_f32_e32 v109, v109
	v_exp_f32_e32 v110, v110
	s_waitcnt lgkmcnt(1)
	v_mfma_f32_32x32x16_bf16 v[130:145], v[98:101], v[162:165], v[130:145]
	s_waitcnt lgkmcnt(0)
	v_mfma_f32_32x32x16_bf16 v[114:129], v[186:189], v[162:165], v[114:129]
	ds_read_b128 v[98:101], v223 offset:32768
	ds_read_b128 v[186:189], v223 offset:40960
	s_waitcnt lgkmcnt(1)
	v_mfma_f32_32x32x16_bf16 v[130:145], v[98:101], v[158:161], v[130:145]
	s_waitcnt lgkmcnt(0)
	v_mfma_f32_32x32x16_bf16 v[114:129], v[186:189], v[158:161], v[114:129]
	ds_read_b128 v[98:101], v224 offset:32768
	ds_read_b128 v[186:189], v224 offset:40960
	s_waitcnt lgkmcnt(1)
	v_mfma_f32_32x32x16_bf16 v[130:145], v[98:101], v[146:149], v[130:145]
	s_waitcnt lgkmcnt(0)
	v_mfma_f32_32x32x16_bf16 v[114:129], v[186:189], v[146:149], v[114:129]
	v_xor_b32_e32 v98, 0x80, v221
	ds_read_b128 v[98:101], v98 offset:32768
	v_xor_b32_e32 v186, 0x80, v221
	ds_read_b128 v[186:189], v186 offset:40960
	s_waitcnt lgkmcnt(1)
	v_mfma_f32_32x32x16_bf16 v[130:145], v[98:101], v[150:153], v[130:145]
	s_waitcnt lgkmcnt(0)
	v_mfma_f32_32x32x16_bf16 v[114:129], v[186:189], v[150:153], v[114:129]
	v_xor_b32_e32 v98, 0x80, v222
	ds_read_b128 v[98:101], v98 offset:32768
	v_xor_b32_e32 v186, 0x80, v222
	ds_read_b128 v[186:189], v186 offset:40960
	s_waitcnt lgkmcnt(1)
	v_mfma_f32_32x32x16_bf16 v[130:145], v[98:101], v[154:157], v[130:145]
	s_waitcnt lgkmcnt(0)
	v_mfma_f32_32x32x16_bf16 v[114:129], v[186:189], v[154:157], v[114:129]
	v_xor_b32_e32 v98, 0x80, v223
	ds_read_b128 v[98:101], v98 offset:32768
	v_xor_b32_e32 v186, 0x80, v223
	ds_read_b128 v[186:189], v186 offset:40960
	s_waitcnt lgkmcnt(1)
	v_mfma_f32_32x32x16_bf16 v[130:145], v[98:101], v[174:177], v[130:145]
	s_waitcnt lgkmcnt(0)
	v_mfma_f32_32x32x16_bf16 v[114:129], v[186:189], v[174:177], v[114:129]
	v_xor_b32_e32 v98, 0x80, v224
	ds_read_b128 v[98:101], v98 offset:32768
	v_xor_b32_e32 v186, 0x80, v224
	ds_read_b128 v[186:189], v186 offset:40960
	s_waitcnt lgkmcnt(1)
	v_mfma_f32_32x32x16_bf16 v[130:145], v[98:101], v[170:173], v[130:145]
	v_exp_f32_e32 v98, v102
	v_exp_f32_e32 v99, v103
	v_exp_f32_e32 v100, v111
	v_exp_f32_e32 v101, v112
	v_exp_f32_e32 v102, v113
	v_add_f32_e32 v2, v98, v2
	v_exp_f32_e32 v103, v183
	v_add_f32_e32 v2, v99, v2
	v_add_f32_e32 v2, v100, v2
	v_add_f32_e32 v2, v101, v2
	v_add_f32_e32 v2, v102, v2
	v_add_f32_e32 v2, v103, v2
	v_add_f32_e32 v2, v104, v2
	v_add_f32_e32 v2, v105, v2
	v_add_f32_e32 v2, v106, v2
	v_exp_f32_e32 v111, v184
	v_add_f32_e32 v2, v107, v2
	s_waitcnt lgkmcnt(0)
	v_mfma_f32_32x32x16_bf16 v[114:129], v[186:189], v[170:173], v[114:129]
	v_exp_f32_e32 v112, v185
	v_add_f32_e32 v2, v108, v2
	v_exp_f32_e32 v113, v182
	v_add_f32_e32 v2, v109, v2
	v_add_f32_e32 v2, v110, v2
	v_add_f32_e32 v2, v111, v2
	v_add_f32_e32 v2, v112, v2
	v_add_f32_e32 v2, v113, v2
	v_mov_b32_e32 v3, v2
	v_cvt_pk_bf16_f32 v182, v82, v83
	v_cvt_pk_bf16_f32 v183, v84, v85
	v_cvt_pk_bf16_f32 v184, v86, v87
	v_cvt_pk_bf16_f32 v185, v88, v89
	v_cvt_pk_bf16_f32 v186, v90, v91
	v_cvt_pk_bf16_f32 v187, v92, v93
	v_cvt_pk_bf16_f32 v188, v94, v95
	v_cvt_pk_bf16_f32 v189, v96, v97
	v_cvt_pk_bf16_f32 v190, v98, v99
	v_cvt_pk_bf16_f32 v191, v100, v101
	v_cvt_pk_bf16_f32 v192, v102, v103
	v_cvt_pk_bf16_f32 v193, v104, v105
	v_cvt_pk_bf16_f32 v194, v106, v107
	v_cvt_pk_bf16_f32 v195, v108, v109
	v_cvt_pk_bf16_f32 v196, v110, v111
	v_cvt_pk_bf16_f32 v197, v112, v113
	s_nop 1
	v_permlane32_swap_b32_e32 v2, v3
	v_permlane32_swap_b32_e32 v182, v184
	v_permlane32_swap_b32_e32 v183, v185
	v_permlane32_swap_b32_e32 v186, v188
	v_permlane32_swap_b32_e32 v187, v189
	v_permlane32_swap_b32_e32 v190, v192
	v_permlane32_swap_b32_e32 v191, v193
	v_permlane32_swap_b32_e32 v194, v196
	v_permlane32_swap_b32_e32 v195, v197
	s_add_i32 s6, s5, 1
	s_cmp_lt_i32 s6, s97
	s_cselect_b64 s[68:69], -1, 0
	s_cmp_ge_i32 s6, s97
	s_cbranch_scc1 .LBB0_550
	v_add_u32_e32 v6, 0x41, v239
	v_mov_b32_e32 v7, v4
	v_add_u32_e32 v8, 0x61, v239
	v_mov_b32_e32 v9, v4
	v_lshlrev_b64 v[14:15], 12, v[6:7]
	v_lshlrev_b64 v[16:17], 12, v[8:9]
	v_add_u32_e32 v198, 0x41, v240
	v_mov_b32_e32 v199, v4
	v_lshl_add_u64 v[6:7], v[206:207], 0, v[14:15]
	v_lshl_add_u64 v[10:11], v[206:207], 0, v[16:17]
	v_lshl_add_u64 v[14:15], v[208:209], 0, v[14:15]
	v_lshl_add_u64 v[178:179], v[208:209], 0, v[16:17]
	v_lshl_add_u64 v[198:199], v[198:199], 2, s[80:81]
	global_load_dwordx4 v[6:9], v[6:7], off
	s_nop 0
	global_load_dwordx4 v[10:13], v[10:11], off
	s_nop 0
	global_load_dwordx4 v[14:17], v[14:15], off
	s_nop 0
	global_load_dwordx4 v[178:181], v[178:179], off
	s_nop 0
	global_load_dword v230, v[198:199], off
	global_load_dword v229, v[198:199], off offset:128

; #define SBAR() do { asm volatile("s_waitcnt vmcnt(0) lgkmcnt(0)" ::: "memory"); __syncthreads(); } while (0)
; #define SBAR() __builtin_amdgcn_sched_barrier(0)
; #define MLOAD_(t, off) do { if (MODE == 1) mk = *(const unsigned long long*)((const char*)(cur.msk + (t)) + (off)); } while (0)
; template <int KB, int MODE>
; __device__ __forceinline__ void qkt(f32x16& p0, f32x16& p1, const char* K_lds, int r32, int hi, const bf16x8* qr, float bz0, float bz1) {
;     p0 = f32x16{}; p1 = f32x16{};
;     if (MODE == 0) {
;         unsigned hm = (unsigned)hi - 1u; asm volatile("" : "+v"(hm));
;         u32x4 ow = {hm & 0x3f803f80u, hm & 0x00003f80u, 0u, 0u};
;         const bf16x8 ones = *reinterpret_cast<bf16x8*>(&ow);
;         p0 = __builtin_amdgcn_mfma_f32_32x32x16_bf16(bias_frag(bz0, hi), ones, p0, 0, 0, 0);
;         p1 = __builtin_amdgcn_mfma_f32_32x32x16_bf16(bias_frag(bz1, hi), ones, p1, 0, 0, 0);
;     }
;     const char* kb[4];
; #pragma unroll
;     for (int dd = 0; dd < 4; ++dd) kb[dd] = K_lds + KB * SHM_K + KSWZ(r32, (dd * 16 + hi * 8) * 2);
; #pragma unroll
;     for (int d0 = 0; d0 < 8; ++d0) { const char* a = kb[d0 & 3] + (d0 >> 2) * 128;
;         bf16x8 b0 = *reinterpret_cast<const bf16x8*>(a);
;         bf16x8 b1 = *reinterpret_cast<const bf16x8*>(a + 32 * 256);
;         p0 = __builtin_amdgcn_mfma_f32_32x32x16_bf16(b0, qr[d0], p0, 0, 0, 0);
;         p1 = __builtin_amdgcn_mfma_f32_32x32x16_bf16(b1, qr[d0], p1, 0, 0, 0); }
; }
; template <int MODE>
; __device__ __forceinline__ void block(const Ref& cur, const Ref& nxt, char* lds, Seam& S) {
;     ...
;     const bool even = (NT & 1) == 0;
;     constexpr bool QPRE = (MODE == 1);
;     int tid2 = tid; asm volatile("" : "+v"(tid2));
;     const int lane2 = tid2 & 63, r32e = lane2 & 31, hie = lane2 >> 5, sre = tid2 >> 4, sce = (tid2 & 15) * 8;
;     const unsigned moffe = (unsigned)((wid * 4 + (r32e >> 3)) * 64 * 8);
;     if (even) { MLOAD_(NT - 1, moffe); SBAR(); qkt<1, MODE>(pB0, pB1, K_lds, r32, hi, S.qr, bz0, bz1); SBAR(); }
.LBB0_559:
	s_bitcmp0_b32 s97, 0
	s_cselect_b64 s[6:7], -1, 0
	v_mov_b32_e32 v178, v0
	s_and_b64 vcc, exec, s[6:7]
	s_cbranch_vccz .LBB0_561
	s_waitcnt vmcnt(1)
	v_bfe_u32 v2, v230, 16, 1
	v_add3_u32 v2, v230, v2, s70
	v_and_b32_e32 v5, 0xffff0000, v2
	v_sub_f32_e32 v5, v230, v5
	v_bfe_u32 v6, v5, 16, 1
	v_add3_u32 v6, v5, v6, s70
	v_and_b32_e32 v6, 0xffff0000, v6
	v_sub_f32_e32 v5, v5, v6
	v_bfe_u32 v7, v5, 16, 1
	v_add3_u32 v5, v5, v7, s70
	v_lshrrev_b32_e32 v5, 16, v5
	v_or_b32_sdwa v2, v6, v2 dst_sel:DWORD dst_unused:UNUSED_PAD src0_sel:DWORD src1_sel:WORD_1
	v_cndmask_b32_e64 v6, 0, v2, s[0:1]
	v_cndmask_b32_e64 v7, 0, v5, s[0:1]
	v_mov_b32_e32 v8, v4
	v_mov_b32_e32 v9, v4
	v_mov_b32_e32 v3, v217
	v_mov_b32_e32 v5, v4
	v_and_b32_e32 v2, 0x3f803f80, v3
	v_and_b32_e32 v3, 0x3f80, v3
	s_nop 1
	v_mfma_f32_32x32x16_bf16 v[82:97], v[6:9], v[2:5], 0
	s_waitcnt vmcnt(0)
	v_bfe_u32 v6, v229, 16, 1
	v_add3_u32 v6, v229, v6, s70
	v_and_b32_e32 v7, 0xffff0000, v6
	v_sub_f32_e32 v7, v229, v7
	v_bfe_u32 v8, v7, 16, 1
	v_add3_u32 v8, v7, v8, s70
	v_and_b32_e32 v8, 0xffff0000, v8
	v_sub_f32_e32 v7, v7, v8
	v_bfe_u32 v9, v7, 16, 1
	v_add3_u32 v7, v7, v9, s70
	v_lshrrev_b32_e32 v7, 16, v7
	v_or_b32_sdwa v6, v8, v6 dst_sel:DWORD dst_unused:UNUSED_PAD src0_sel:DWORD src1_sel:WORD_1
	v_cndmask_b32_e64 v6, 0, v6, s[0:1]
	v_cndmask_b32_e64 v7, 0, v7, s[0:1]
	v_mov_b32_e32 v8, v4
	v_mov_b32_e32 v9, v4
	s_nop 1
	v_mfma_f32_32x32x16_bf16 v[98:113], v[6:9], v[2:5], 0
	ds_read_b128 v[6:9], v221 offset:49152
	v_xor_b32_e32 v10, 0x80, v221
	ds_read_b128 v[10:13], v10 offset:49152
	s_waitcnt lgkmcnt(1)
	v_mfma_f32_32x32x16_bf16 v[82:97], v[6:9], v[166:169], v[82:97]
	ds_read_b128 v[6:9], v221 offset:57344
	v_xor_b32_e32 v14, 0x80, v221
	ds_read_b128 v[14:17], v14 offset:57344
	s_waitcnt lgkmcnt(1)
	v_mfma_f32_32x32x16_bf16 v[98:113], v[6:9], v[166:169], v[98:113]
	ds_read_b128 v[6:9], v222 offset:49152
	v_xor_b32_e32 v114, 0x80, v222
	ds_read_b128 v[114:117], v114 offset:49152
	s_waitcnt lgkmcnt(1)
	v_mfma_f32_32x32x16_bf16 v[82:97], v[6:9], v[162:165], v[82:97]
	ds_read_b128 v[6:9], v222 offset:57344
	v_xor_b32_e32 v118, 0x80, v222
	ds_read_b128 v[118:121], v118 offset:57344
	s_waitcnt lgkmcnt(1)
	v_mfma_f32_32x32x16_bf16 v[98:113], v[6:9], v[162:165], v[98:113]
	ds_read_b128 v[6:9], v223 offset:49152
	v_xor_b32_e32 v122, 0x80, v223
	ds_read_b128 v[122:125], v122 offset:49152
	s_waitcnt lgkmcnt(1)
	v_mfma_f32_32x32x16_bf16 v[82:97], v[6:9], v[158:161], v[82:97]
	ds_read_b128 v[6:9], v223 offset:57344
	v_xor_b32_e32 v126, 0x80, v223
	ds_read_b128 v[126:129], v126 offset:57344
	s_waitcnt lgkmcnt(1)
	v_mfma_f32_32x32x16_bf16 v[98:113], v[6:9], v[158:161], v[98:113]
	ds_read_b128 v[6:9], v224 offset:49152
	v_xor_b32_e32 v158, 0x80, v224
	ds_read_b128 v[158:161], v158 offset:49152
	s_waitcnt lgkmcnt(1)
	v_mfma_f32_32x32x16_bf16 v[82:97], v[6:9], v[146:149], v[82:97]
	ds_read_b128 v[6:9], v224 offset:57344
	v_xor_b32_e32 v162, 0x80, v224
	ds_read_b128 v[162:165], v162 offset:57344
	s_waitcnt lgkmcnt(1)
	v_mfma_f32_32x32x16_bf16 v[98:113], v[6:9], v[146:149], v[98:113]
	v_mfma_f32_32x32x16_bf16 v[82:97], v[10:13], v[150:153], v[82:97]
	v_mfma_f32_32x32x16_bf16 v[98:113], v[14:17], v[150:153], v[98:113]
	v_mfma_f32_32x32x16_bf16 v[82:97], v[114:117], v[154:157], v[82:97]
	v_mfma_f32_32x32x16_bf16 v[98:113], v[118:121], v[154:157], v[98:113]
	v_mfma_f32_32x32x16_bf16 v[82:97], v[122:125], v[174:177], v[82:97]
	v_mfma_f32_32x32x16_bf16 v[98:113], v[126:129], v[174:177], v[98:113]
	v_mfma_f32_32x32x16_bf16 v[82:97], v[158:161], v[170:173], v[82:97]
	s_waitcnt lgkmcnt(0)
	v_mfma_f32_32x32x16_bf16 v[98:113], v[162:165], v[170:173], v[98:113]

; __device__ __forceinline__ int v_st(int k, int c) { const int kk = (k & ~0xC) | ((k & 4) << 1) | ((k & 8) >> 1); return ((kk >> 3) * 4 + (c >> 5)) * 512 + ((kk & 7) * 32 + (c & 31)) * 2; }
; __device__ __forceinline__ int v_rd_base(int lane) { return ((lane & 3) << 3) | (((lane >> 2) & 3) << 6) | (((lane >> 4) & 1) << 5) | (((lane >> 5) & 1) << 8); }
; #define VMW() asm volatile("s_waitcnt vmcnt(0)" ::: "memory")
; #define SLOAD_H(Kp, Vp, k0) do { S.st_v0 = LD8(ROW(Vp, k0, sr)); S.st_v1 = LD8(ROW(Vp, k0, 32 + sr));              \
;                          S.st_k0 = LD8(ROW(Kp, k0, sr)); S.st_k1 = LD8(ROW(Kp, k0, 32 + sr)); } while (0)
; #define SWRITE_HK(bf) do { *(bf16x8*)(K_lds + (bf) * SHM_K + kws) = S.st_k0; *(bf16x8*)(K_lds + (bf) * SHM_K + kws + 32 * 256) = S.st_k1; } while (0)
; template <int MODE>
; __device__ __forceinline__ void prime(const Ref& cur, char* lds, Seam& S) {
;     constexpr int PKV = MODE == 0 ? 2048 : 512;
;     const int tid = threadIdx.x, wid = __builtin_amdgcn_readfirstlane(tid >> 6), lane = tid & 63, r32 = lane & 31, hi = lane >> 5;
;     const int sr = tid >> 4, sc = (tid & 15) * 8, kws = KSWZ(sr, sc * 2); char* K_lds = lds + 2 * SHM_V;
;     const bf16_t* qp = cur.Q + qrow_off<MODE>(wid * QBLK + r32) + hi * 8;
; #pragma unroll
;     for (int d0 = 0; d0 < 8; ++d0) S.qr[d0] = LD8(qp + d0 * 16);
;     SLOAD_H(cur.K, cur.V, 0); VMW(); SWRITE_HK(0);
;     __syncthreads();
; }
; template <int MODE>
; __device__ __forceinline__ void block(const Ref& cur, const Ref& nxt, char* lds, Seam& S) {
;     constexpr int PKV = MODE == 0 ? 2048 : 512;
;     const int tid = threadIdx.x, wid = __builtin_amdgcn_readfirstlane(tid >> 6), lane = tid & 63, r32 = lane & 31, hi = lane >> 5;
;     const int NT = cur.NT;
;     const int qlo = cur.P0 + wid * QBLK, qm = qlo + r32 - 4 * hi;
;     char* V_lds = lds; char* K_lds = lds + 2 * SHM_V;
;     float* ws = (float*)(lds + 2 * SHM_V + 2 * SHM_K) + wid * 64; float* li_l = ws, * al_l = ws + 32;
;     float m_reg = -1e30f, l_reg = 0; f32x16 o[4] = {};
;     const int sr = tid >> 4, sc = (tid & 15) * 8, vst0 = v_st(sr, sc), vst1 = v_st(32 + sr, sc), kws = KSWZ(sr, sc * 2);
;     const int vb0 = (int)(uintptr_t)V_lds + v_rd_base(lane);
.LBB0_1212:
	v_readlane_b32 s2, v254, 11
	v_readlane_b32 s3, v254, 12
	s_cmp_lt_i32 s2, 6
	s_cselect_b64 s[2:3], -1, 0
	s_and_b64 s[2:3], s[2:3], s[0:1]
	s_andn2_b64 vcc, exec, s[2:3]
	s_cbranch_vccnz .LBB0_1386
	s_load_dword s10, s[56:57], 0xe0
	s_mov_b64 s[0:1], s[56:57]
	s_waitcnt lgkmcnt(0)
	s_abs_i32 s4, s10
	v_cvt_f32_u32_e32 v1, s4
	s_sub_i32 s6, 0, s4
	s_ashr_i32 s5, s10, 31
	v_rcp_iflag_f32_e32 v1, v1
	s_nop 0
	v_mul_f32_e32 v1, 0x4f7ffffe, v1
	v_cvt_u32_f32_e32 v1, v1
	s_nop 0
	v_readfirstlane_b32 s7, v1
	s_mul_i32 s6, s6, s7
	s_mul_hi_u32 s6, s7, s6
	s_add_i32 s7, s7, s6
	s_lshr_b32 s6, s7, 22
	s_mul_i32 s7, s6, s4
	s_sub_i32 s7, 0x400, s7
	s_add_i32 s8, s6, 1
	s_sub_i32 s9, s7, s4
	s_cmp_ge_u32 s7, s4
	s_cselect_b32 s6, s8, s6
	s_cselect_b32 s7, s9, s7
	s_add_i32 s8, s6, 1
	s_cmp_ge_u32 s7, s4
	s_cselect_b32 s4, s8, s6
	s_xor_b32 s4, s4, s5
	s_sub_i32 s30, s4, s5
	s_mul_i32 s4, s30, s10
	s_cmpk_lg_i32 s4, 0x400
	s_cbranch_scc1 .LBB0_1386
	s_load_dwordx2 s[0:1], s[0:1], 0xd0
	v_mov_b32_e32 v3, 0
	v_mov_b32_e32 v199, v3
	s_mov_b32 s36, 0x8000
	s_waitcnt lgkmcnt(0)
	s_add_u32 s31, s0, 0x8a00000
	s_addc_u32 s33, s1, 0
	s_add_u32 s34, s0, 0x6a00000
	s_addc_u32 s35, s1, 0
	s_ashr_i32 s6, s74, 4
	s_lshl_b32 s4, s74, 5
	s_and_b32 s4, s4, 32
	s_lshl_b32 s5, s6, 6
	s_sub_i32 s4, s4, s5
	s_addk_i32 s4, 0xfc0
	s_lshl_b32 s5, s74, 10
	s_bfe_u32 s10, s74, 0x10001
	s_and_b32 s7, s5, 0x3000
	s_ashr_i32 s5, s4, 31
	s_add_u32 s8, s4, s7
	s_addc_u32 s9, s5, 0
	s_lshl_b64 s[4:5], s[8:9], 12
	s_add_u32 s4, s31, s4
	s_addc_u32 s5, s33, s5
	s_lshl_b32 s11, s10, 11
	s_add_u32 s4, s4, s11
	s_addc_u32 s5, s5, 0
	s_lshl_b32 s7, s7, 10
	s_add_u32 s7, s34, s7
	s_addc_u32 s11, s35, 0
	s_lshl_b32 s12, s10, 8
	s_add_u32 s24, s7, s12
	s_addc_u32 s25, s11, 0
	s_add_u32 s26, s24, 0x200
	v_readfirstlane_b32 s7, v0
	s_addc_u32 s27, s25, 0
	s_lshr_b32 s7, s7, 1
	s_and_b32 s7, s7, 0x7fffffe0
	v_and_or_b32 v1, v0, 24, s7
	v_lshrrev_b32_e32 v2, 3, v1
	v_lshlrev_b64 v[4:5], 12, v[2:3]
	v_lshlrev_b32_e32 v1, 8, v0
	v_lshl_add_u64 v[4:5], s[4:5], 0, v[4:5]
	v_and_b32_e32 v2, 0x700, v1
	v_lshrrev_b32_e32 v1, 1, v0
	v_lshl_add_u64 v[4:5], v[4:5], 0, v[2:3]
	v_and_b32_e32 v2, 16, v1
	v_lshl_add_u64 v[6:7], v[4:5], 0, v[2:3]
	v_lshrrev_b32_e32 v1, 4, v0
	v_lshlrev_b32_e32 v4, 3, v0
	v_and_b32_e32 v5, 0x78, v4
	v_lshlrev_b32_e32 v2, 10, v1
	global_load_dwordx4 v[158:161], v[6:7], off
	global_load_dwordx4 v[154:157], v[6:7], off offset:32
	global_load_dwordx4 v[150:153], v[6:7], off offset:64
	global_load_dwordx4 v[146:149], v[6:7], off offset:96
	v_lshlrev_b32_e32 v198, 1, v5
	v_lshl_add_u64 v[8:9], s[24:25], 0, v[2:3]
	v_lshl_add_u64 v[8:9], v[8:9], 0, v[198:199]
	global_load_dwordx4 v[130:133], v[8:9], off offset:512
	global_load_dwordx4 v[138:141], v[8:9], off
	v_or_b32_e32 v2, 0x8000, v2
	v_lshl_add_u64 v[10:11], s[26:27], 0, v[2:3]
	v_lshl_add_u64 v[10:11], v[10:11], 0, v[198:199]
	v_add_co_u32_e32 v8, vcc, 0x8000, v8
	v_and_b32_e32 v2, 0xf0, v0
	s_nop 0
	v_addc_co_u32_e32 v9, vcc, 0, v9, vcc
	global_load_dwordx4 v[134:137], v[10:11], off
	global_load_dwordx4 v[142:145], v[8:9], off
	global_load_dwordx4 v[174:177], v[6:7], off offset:128
	global_load_dwordx4 v[170:173], v[6:7], off offset:160
	global_load_dwordx4 v[166:169], v[6:7], off offset:192
	global_load_dwordx4 v[162:165], v[6:7], off offset:224
	v_lshlrev_b32_e32 v6, 8, v1
	s_waitcnt vmcnt(0)
	v_bitop3_b32 v2, v198, v6, v2 bitop3:0xde
	s_mov_b32 s7, 0
	v_add_u32_e32 v211, 0, v2
	s_cmp_lt_i32 s30, 1
	s_waitcnt vmcnt(0)
	ds_write_b128 v211, v[138:141] offset:32768
	ds_write_b128 v211, v[142:145] offset:40960
	s_waitcnt lgkmcnt(0)
	s_barrier
	s_cbranch_scc1 .LBB0_1386
	s_lshl_b64 s[12:13], s[8:9], 11
	s_lshl_b32 s10, s10, 10
	s_add_u32 s37, s0, 0xca00000
	s_addc_u32 s38, s1, 0
	s_add_u32 s39, s0, 0x5a00000
	s_addc_u32 s40, s1, 0
	s_sub_i32 s20, 64, s6
	s_lshl_b64 s[0:1], s[8:9], 9
	s_add_u32 s22, s39, s0
	s_addc_u32 s23, s40, s1
	s_lshl_b64 s[0:1], s[12:13], 1
	s_add_u32 s0, s37, s0
	s_addc_u32 s1, s38, s1
	s_lshl_b32 s6, s10, 1
	s_add_u32 s18, s0, s6
	v_lshlrev_b32_e32 v2, 1, v1
	s_addc_u32 s19, s1, 0
	s_load_dword s1, s[56:57], 0xe0
	v_and_b32_e32 v2, 8, v2
	v_or_b32_e32 v11, 32, v1
	v_and_or_b32 v8, v1, 16, v2
	v_and_or_b32 v2, v11, 48, v2
	v_lshrrev_b32_e32 v9, 5, v0
	v_lshrrev_b32_e32 v8, 1, v8
	v_lshrrev_b32_e32 v5, 5, v5
	v_bfe_u32 v10, v0, 4, 2
	v_lshrrev_b32_e32 v2, 1, v2
	v_or_b32_e32 v8, v8, v5
	v_and_or_b32 v9, v9, 4, v10
	v_or_b32_e32 v2, v2, v5
	s_not_b32 s0, s74
	v_lshlrev_b32_e32 v8, 9, v8
	v_lshlrev_b32_e32 v9, 6, v9
	v_and_b32_e32 v10, 48, v198
	v_lshlrev_b32_e32 v2, 9, v2
	s_waitcnt lgkmcnt(0)
	s_add_i32 s9, s1, s0
	v_or3_b32 v8, v8, v9, v10
	v_or3_b32 v5, v2, v9, v10
	v_lshlrev_b32_e32 v9, 4, v0
	v_lshlrev_b32_e32 v10, 1, v0
	v_and_b32_e32 v2, 0xc0, v9
	v_and_b32_e32 v10, 32, v10
	v_and_b32_e32 v4, 0x118, v4
	s_cmp_lg_u32 0, -1
	v_lshlrev_b32_e32 v6, 9, v1
	v_and_b32_e32 v212, 31, v0
	v_lshrrev_b32_e32 v7, 5, v232
	v_or3_b32 v2, v10, v2, v4
	s_cselect_b32 s0, 0, 0
	v_add_u32_e32 v213, s0, v2
	v_or_b32_e32 v2, 0x8000, v6
	v_or_b32_e32 v4, 0xc000, v6
	v_lshlrev_b32_e32 v6, 8, v212
	v_lshlrev_b32_e32 v10, 4, v7
	v_and_b32_e32 v9, 0xf0, v9
	v_bitop3_b32 v11, v10, v6, v9 bitop3:0xde
	v_or_b32_e32 v12, 32, v10
	v_or_b32_e32 v13, 64, v10
	v_or_b32_e32 v10, 0x60, v10
	v_bitop3_b32 v12, v12, v6, v9 bitop3:0xde
	v_bitop3_b32 v13, v13, v6, v9 bitop3:0xde
	v_bitop3_b32 v6, v10, v6, v9 bitop3:0xde
	v_or_b32_e32 v216, 0x80, v1
	v_mbcnt_lo_u32_b32 v1, -1, 0
	v_bfe_u32 v214, v0, 3, 2
	v_lshlrev_b32_e32 v215, 2, v7
	v_cmp_gt_u32_e64 s[0:1], 32, v232
	v_lshlrev_b32_e32 v200, 1, v2
	v_lshlrev_b32_e32 v202, 1, v4
	s_mov_b32 s41, 0x41000000
	s_mov_b32 s8, 0x3e0293ee
	v_mbcnt_hi_u32_b32 v217, -1, v1
	v_add_u32_e32 v219, 0, v8
	v_add_u32_e32 v220, 0, v5
	v_add_u32_e32 v221, 0, v11
	v_add_u32_e32 v222, 0, v12
	v_add_u32_e32 v223, 0, v13
	v_add_u32_e32 v224, 0, v6
	v_mov_b32_e32 v225, 0xff800000
	s_mov_b32 s6, 0
	s_mov_b64 s[16:17], s[22:23]
	s_mov_b64 s[10:11], s[18:19]
	s_mov_b64 s[14:15], s[26:27]
	s_mov_b64 s[12:13], s[24:25]
	s_branch .LBB0_1217

; __device__ __forceinline__ void mask_bits(f32x16& p0, f32x16& p1, unsigned long long mk, int hi) {
;     const float NEG = -__builtin_inff();
;     const unsigned lo = (unsigned)mk >> (4 * hi), hh = (unsigned)(mk >> 32) >> (4 * hi);
; #pragma unroll
;     for (int r = 0; r < 16; ++r) {
;         const int c = (r & 3) + 8 * (r >> 2);
;         if (!(lo & (1u << c))) p0[r] = NEG;
;         if (!(hh & (1u << c))) p1[r] = NEG;
;     }
; }
; __device__ __forceinline__ void partialSM(f32x16& p0, f32x16& p1, float& m_reg, float& mn, float& alpha) {
;     float pmax = p0[0];
; #pragma unroll
;     for (int r = 1; r < 16; ++r) pmax = fmaxf(pmax, p0[r]);
; #pragma unroll
;     for (int r = 0; r < 16; ++r) pmax = fmaxf(pmax, p1[r]);
;     { auto rr = __builtin_amdgcn_permlane32_swap(__float_as_uint(pmax), __float_as_uint(pmax), false, false);
;       pmax = fmaxf(__uint_as_float(rr[0]), __uint_as_float(rr[1])); }
; template <int KB, int MODE>
; __device__ __forceinline__ void qkt(f32x16& p0, f32x16& p1, const char* K_lds, int r32, int hi, const bf16x8* qr, float bz0, float bz1) {
;     p0 = f32x16{}; p1 = f32x16{};
;     if (MODE == 0) {
;         unsigned hm = (unsigned)hi - 1u; asm volatile("" : "+v"(hm));
;         u32x4 ow = {hm & 0x3f803f80u, hm & 0x00003f80u, 0u, 0u};
;         const bf16x8 ones = *reinterpret_cast<bf16x8*>(&ow);
;         p0 = __builtin_amdgcn_mfma_f32_32x32x16_bf16(bias_frag(bz0, hi), ones, p0, 0, 0, 0);
;         p1 = __builtin_amdgcn_mfma_f32_32x32x16_bf16(bias_frag(bz1, hi), ones, p1, 0, 0, 0);
;     }
;     const char* kb[4];
; #pragma unroll
;     for (int dd = 0; dd < 4; ++dd) kb[dd] = K_lds + KB * SHM_K + KSWZ(r32, (dd * 16 + hi * 8) * 2);
; #pragma unroll
;     for (int d0 = 0; d0 < 8; ++d0) { const char* a = kb[d0 & 3] + (d0 >> 2) * 128;
;         bf16x8 b0 = *reinterpret_cast<const bf16x8*>(a);
;         bf16x8 b1 = *reinterpret_cast<const bf16x8*>(a + 32 * 256);
;         p0 = __builtin_amdgcn_mfma_f32_32x32x16_bf16(b0, qr[d0], p0, 0, 0, 0);
;         p1 = __builtin_amdgcn_mfma_f32_32x32x16_bf16(b1, qr[d0], p1, 0, 0, 0); }
; }
; template <int MODE>
; __device__ __forceinline__ void block(const Ref& cur, const Ref& nxt, char* lds, Seam& S) {
;     ...
;     MLOAD(0);
;     SBAR(); qkt<0, MODE>(pA0, pA1, K_lds, r32, hi, S.qr, bz0, bz1);
;     if (NT > 1) BLOAD(bz0, bz1, 1);
;     MASKT(pA0, pA1, 0); partialSM(pA0, pA1, m_reg, mnA, alA);
.LBB0_1221:
	s_lshr_b32 s44, s21, 6
	s_lshl_b32 s6, s44, 2
	v_or_b32_e32 v1, s6, v214
	v_lshlrev_b32_e32 v2, 9, v1
	global_load_dwordx2 v[204:205], v2, s[22:23]
	ds_read_b128 v[4:7], v221 offset:32768
	v_xor_b32_e32 v36, 0x80, v221
	ds_read_b128 v[36:39], v36 offset:32768
	ds_read_b128 v[20:23], v221 offset:40960
	v_xor_b32_e32 v40, 0x80, v221
	ds_read_b128 v[40:43], v40 offset:40960
	ds_read_b128 v[44:47], v222 offset:32768
	v_xor_b32_e32 v48, 0x80, v222
	ds_read_b128 v[48:51], v48 offset:32768
	s_waitcnt vmcnt(8) lgkmcnt(5)
	v_mfma_f32_32x32x16_bf16 v[4:19], v[4:7], v[158:161], 0
	s_waitcnt lgkmcnt(3)
	v_mfma_f32_32x32x16_bf16 v[20:35], v[20:23], v[158:161], 0
	s_waitcnt vmcnt(7) lgkmcnt(1)
	v_mfma_f32_32x32x16_bf16 v[4:19], v[44:47], v[154:157], v[4:19]
	ds_read_b128 v[44:47], v222 offset:40960
	v_xor_b32_e32 v52, 0x80, v222
	ds_read_b128 v[52:55], v52 offset:40960
	s_waitcnt lgkmcnt(1)
	v_mfma_f32_32x32x16_bf16 v[20:35], v[44:47], v[154:157], v[20:35]
	ds_read_b128 v[44:47], v223 offset:32768
	v_xor_b32_e32 v56, 0x80, v223
	ds_read_b128 v[56:59], v56 offset:32768
	s_waitcnt vmcnt(6) lgkmcnt(1)
	v_mfma_f32_32x32x16_bf16 v[4:19], v[44:47], v[150:153], v[4:19]
	ds_read_b128 v[44:47], v223 offset:40960
	v_xor_b32_e32 v60, 0x80, v223
	ds_read_b128 v[60:63], v60 offset:40960
	s_waitcnt lgkmcnt(1)
	v_mfma_f32_32x32x16_bf16 v[20:35], v[44:47], v[150:153], v[20:35]
	ds_read_b128 v[44:47], v224 offset:32768
	v_xor_b32_e32 v64, 0x80, v224
	ds_read_b128 v[64:67], v64 offset:32768
	s_waitcnt vmcnt(5) lgkmcnt(1)
	v_mfma_f32_32x32x16_bf16 v[4:19], v[44:47], v[146:149], v[4:19]
	ds_read_b128 v[44:47], v224 offset:40960
	v_xor_b32_e32 v68, 0x80, v224
	ds_read_b128 v[68:71], v68 offset:40960
	s_waitcnt lgkmcnt(1)
	v_mfma_f32_32x32x16_bf16 v[20:35], v[44:47], v[146:149], v[20:35]
	s_waitcnt vmcnt(4)
	v_mfma_f32_32x32x16_bf16 v[4:19], v[36:39], v[174:177], v[4:19]
	s_waitcnt vmcnt(0)
	v_lshrrev_b32_e32 v36, v215, v204
	v_lshrrev_b32_e32 v37, v215, v205
	v_mfma_f32_32x32x16_bf16 v[20:35], v[40:43], v[174:177], v[20:35]
	v_mfma_f32_32x32x16_bf16 v[4:19], v[48:51], v[170:173], v[4:19]
	v_mfma_f32_32x32x16_bf16 v[20:35], v[52:55], v[170:173], v[20:35]
	v_mfma_f32_32x32x16_bf16 v[4:19], v[56:59], v[166:169], v[4:19]
	v_mfma_f32_32x32x16_bf16 v[20:35], v[60:63], v[166:169], v[20:35]
	v_mfma_f32_32x32x16_bf16 v[4:19], v[64:67], v[162:165], v[4:19]
	s_waitcnt lgkmcnt(0)
	v_mfma_f32_32x32x16_bf16 v[20:35], v[68:71], v[162:165], v[20:35]
	s_nop 9
	v_bfe_i32 v1, v36, 0, 1
	v_bfi_b32 v1, v1, v4, v225
	v_bfe_i32 v4, v37, 0, 1
	v_bfi_b32 v4, v4, v20, v225
	v_bfe_i32 v20, v36, 1, 1
	v_bfi_b32 v20, v20, v5, v225
	v_bfe_i32 v5, v37, 1, 1
	v_bfi_b32 v5, v5, v21, v225
	v_bfe_i32 v21, v36, 2, 1
	v_bfi_b32 v21, v21, v6, v225
	v_bfe_i32 v6, v37, 2, 1
	v_bfi_b32 v6, v6, v22, v225
	v_bfe_i32 v22, v36, 3, 1
	v_bfi_b32 v22, v22, v7, v225
	v_bfe_i32 v7, v37, 3, 1
	v_bfi_b32 v7, v7, v23, v225
	v_bfe_i32 v23, v36, 8, 1
	v_bfi_b32 v23, v23, v8, v225
	v_bfe_i32 v8, v37, 8, 1
	v_bfi_b32 v8, v8, v24, v225
	v_bfe_i32 v24, v36, 9, 1
	v_bfi_b32 v24, v24, v9, v225
	v_bfe_i32 v9, v37, 9, 1
	v_bfi_b32 v9, v9, v25, v225
	v_bfe_i32 v25, v36, 10, 1
	v_bfi_b32 v25, v25, v10, v225
	v_bfe_i32 v10, v37, 10, 1
	v_bfi_b32 v10, v10, v26, v225
	v_bfe_i32 v26, v36, 11, 1
	v_bfi_b32 v26, v26, v11, v225
	v_bfe_i32 v11, v37, 11, 1
	v_bfi_b32 v11, v11, v27, v225
	v_bfe_i32 v27, v36, 16, 1
	v_bfi_b32 v27, v27, v12, v225
	v_bfe_i32 v12, v37, 16, 1
	v_bfi_b32 v12, v12, v28, v225
	v_bfe_i32 v28, v36, 17, 1
	v_bfi_b32 v28, v28, v13, v225
	v_bfe_i32 v13, v37, 17, 1
	v_bfi_b32 v13, v13, v29, v225
	v_bfe_i32 v29, v36, 18, 1
	v_bfi_b32 v29, v29, v14, v225
	v_bfe_i32 v14, v37, 18, 1
	v_bfi_b32 v14, v14, v30, v225
	v_bfe_i32 v30, v36, 19, 1
	v_bfi_b32 v30, v30, v15, v225
	v_bfe_i32 v15, v37, 19, 1
	v_bfi_b32 v15, v15, v31, v225
	v_bfe_i32 v31, v36, 24, 1
	v_bfi_b32 v31, v31, v16, v225
	v_bfe_i32 v16, v37, 24, 1
	v_bfi_b32 v16, v16, v32, v225
	v_bfe_i32 v32, v36, 25, 1
	v_bfi_b32 v32, v32, v17, v225
	v_bfe_i32 v17, v37, 25, 1
	v_bfi_b32 v17, v17, v33, v225
	v_bfe_i32 v33, v36, 26, 1
	v_bfi_b32 v33, v33, v18, v225
	v_bfe_i32 v18, v37, 26, 1
	v_bfi_b32 v18, v18, v34, v225
	v_and_b32_e32 v34, 0x8000000, v36
	v_cmp_ne_u32_e32 vcc, 0, v34
	v_max_f32_e32 v36, v1, v1
	s_nop 0
	s_nop 1
	v_cndmask_b32_e32 v34, v225, v19, vcc
	v_bfe_i32 v19, v37, 27, 1
	v_bfi_b32 v19, v19, v35, v225
	v_max_f32_e32 v35, v20, v20
	v_max_f32_e32 v35, v36, v35
	v_max3_f32 v35, v35, v21, v22
	v_max3_f32 v35, v35, v23, v24
	v_max3_f32 v35, v35, v25, v26
	v_max3_f32 v35, v35, v27, v28
	v_max3_f32 v35, v35, v29, v30
	v_max3_f32 v35, v35, v31, v32
	v_max3_f32 v35, v35, v33, v34
	v_max3_f32 v35, v35, v4, v5
	v_max3_f32 v35, v35, v6, v7
	v_max3_f32 v35, v35, v8, v9
	v_max3_f32 v35, v35, v10, v11
	v_max3_f32 v35, v35, v12, v13
	v_max3_f32 v35, v35, v14, v15
	v_max3_f32 v35, v35, v16, v17
	v_max3_f32 v35, v35, v18, v19
	v_mov_b32_e32 v36, v35
	s_nop 1
	v_permlane32_swap_b32_e32 v35, v36
	v_max_f32_e32 v36, v36, v36
	v_max_f32_e32 v35, v35, v35
	v_max_f32_e32 v35, v35, v36
	v_add_f32_e32 v36, 0x7149f2ca, v35
	v_mul_f32_e32 v36, 0x3db504f3, v36
	v_cmp_ge_f32_e32 vcc, s41, v36
	s_cmp_eq_u64 vcc, exec
	s_cbranch_scc0 .LBB0_1384
	v_mov_b32_e32 v203, 1.0
	v_mov_b32_e32 v201, 0xf149f2ca
	s_andn2_b64 vcc, exec, s[28:29]
	s_cbranch_vccnz .LBB0_1224

; __device__ __forceinline__ void finishSM(f32x16& p0, f32x16& p1, float alpha, float& l_reg, bf16x8& pa0, bf16x8& pa1, bf16x8& pa2, bf16x8& pa3) {
; #pragma unroll
;     for (int r = 0; r < 16; ++r) p1[r] = __builtin_amdgcn_exp2f(p1[r]);
;     float ps = 0;
; #pragma unroll
;     for (int r = 0; r < 16; ++r) ps += p0[r];
; #pragma unroll
;     for (int r = 0; r < 16; ++r) ps += p1[r];
;     { auto rr = __builtin_amdgcn_permlane32_swap(__float_as_uint(ps), __float_as_uint(ps), false, false);
;       ps = __uint_as_float(rr[0]) + __uint_as_float(rr[1]); }
;     l_reg = l_reg * alpha + ps;
;     ...
;     PK4(p0, 0, pa0); PK4(p0, 8, pa1); PK4(p1, 0, pa2); PK4(p1, 8, pa3);
; template <int KB, int MODE>
; __device__ __forceinline__ void qkt(f32x16& p0, f32x16& p1, const char* K_lds, int r32, int hi, const bf16x8* qr, float bz0, float bz1) {
;     p0 = f32x16{}; p1 = f32x16{};
;     if (MODE == 0) {
;         unsigned hm = (unsigned)hi - 1u; asm volatile("" : "+v"(hm));
;         u32x4 ow = {hm & 0x3f803f80u, hm & 0x00003f80u, 0u, 0u};
;         const bf16x8 ones = *reinterpret_cast<bf16x8*>(&ow);
;         p0 = __builtin_amdgcn_mfma_f32_32x32x16_bf16(bias_frag(bz0, hi), ones, p0, 0, 0, 0);
;         p1 = __builtin_amdgcn_mfma_f32_32x32x16_bf16(bias_frag(bz1, hi), ones, p1, 0, 0, 0);
;     }
;     const char* kb[4];
; #pragma unroll
;     for (int dd = 0; dd < 4; ++dd) kb[dd] = K_lds + KB * SHM_K + KSWZ(r32, (dd * 16 + hi * 8) * 2);
; #pragma unroll
;     for (int d0 = 0; d0 < 8; ++d0) { const char* a = kb[d0 & 3] + (d0 >> 2) * 128;
;         bf16x8 b0 = *reinterpret_cast<const bf16x8*>(a);
;         bf16x8 b1 = *reinterpret_cast<const bf16x8*>(a + 32 * 256);
;         p0 = __builtin_amdgcn_mfma_f32_32x32x16_bf16(b0, qr[d0], p0, 0, 0, 0);
;         p1 = __builtin_amdgcn_mfma_f32_32x32x16_bf16(b1, qr[d0], p1, 0, 0, 0); }
; }
.LBB0_1228:
	global_load_dwordx2 v[132:133], v[208:209], off
	ds_read_b128 v[4:7], v221 offset:49152
	v_xor_b32_e32 v8, 0x80, v221
	ds_read_b128 v[8:11], v8 offset:49152
	v_add_f32_e32 v129, 0, v128
	v_exp_f32_e32 v186, v186
	v_exp_f32_e32 v187, v187
	s_waitcnt lgkmcnt(1)
	v_mfma_f32_32x32x16_bf16 v[82:97], v[4:7], v[158:161], 0
	ds_read_b128 v[4:7], v222 offset:49152
	v_xor_b32_e32 v12, 0x80, v222
	ds_read_b128 v[12:15], v12 offset:49152
	v_exp_f32_e32 v184, v184
	v_exp_f32_e32 v185, v185
	v_exp_f32_e32 v182, v182
	v_exp_f32_e32 v183, v183
	v_exp_f32_e32 v180, v180
	v_exp_f32_e32 v181, v181
	s_waitcnt lgkmcnt(1)
	v_mfma_f32_32x32x16_bf16 v[82:97], v[4:7], v[154:157], v[82:97]
	ds_read_b128 v[4:7], v221 offset:57344
	v_xor_b32_e32 v134, 0x80, v221
	ds_read_b128 v[134:137], v134 offset:57344
	v_exp_f32_e32 v178, v178
	v_exp_f32_e32 v179, v179
	s_waitcnt lgkmcnt(1)
	v_mfma_f32_32x32x16_bf16 v[98:113], v[4:7], v[158:161], 0
	ds_read_b128 v[4:7], v222 offset:57344
	v_xor_b32_e32 v138, 0x80, v222
	ds_read_b128 v[138:141], v138 offset:57344
	s_waitcnt lgkmcnt(1)
	v_mfma_f32_32x32x16_bf16 v[98:113], v[4:7], v[154:157], v[98:113]
	ds_read_b128 v[4:7], v223 offset:49152
	v_xor_b32_e32 v142, 0x80, v223
	ds_read_b128 v[142:145], v142 offset:49152
	s_waitcnt lgkmcnt(1)
	v_mfma_f32_32x32x16_bf16 v[82:97], v[4:7], v[150:153], v[82:97]
	ds_read_b128 v[4:7], v223 offset:57344
	v_xor_b32_e32 v194, 0x80, v223
	ds_read_b128 v[194:197], v194 offset:57344
	s_waitcnt lgkmcnt(1)
	v_mfma_f32_32x32x16_bf16 v[98:113], v[4:7], v[150:153], v[98:113]
	ds_read_b128 v[4:7], v224 offset:49152
	v_xor_b32_e32 v230, 0x80, v224
	ds_read_b128 v[230:233], v230 offset:49152
	ds_read_b128 v[234:237], v224 offset:57344
	v_xor_b32_e32 v238, 0x80, v224
	ds_read_b128 v[238:241], v238 offset:57344
	v_cvt_pk_bf16_f32 v128, v128, v1
	v_add_f32_e32 v1, v1, v129
	v_add_f32_e32 v1, v126, v1
	v_add_f32_e32 v1, v123, v1
	v_add_f32_e32 v1, v122, v1
	v_add_f32_e32 v1, v125, v1
	s_waitcnt lgkmcnt(3)
	v_mfma_f32_32x32x16_bf16 v[82:97], v[4:7], v[146:149], v[82:97]
	v_add_f32_e32 v1, v124, v1
	v_add_f32_e32 v1, v127, v1
	v_add_f32_e32 v1, v114, v1
	v_add_f32_e32 v1, v115, v1
	v_add_f32_e32 v1, v116, v1
	v_add_f32_e32 v1, v117, v1
	v_exp_f32_e32 v4, v192
	s_waitcnt lgkmcnt(1)
	v_mfma_f32_32x32x16_bf16 v[98:113], v[234:237], v[146:149], v[98:113]
	v_add_f32_e32 v1, v118, v1
	v_exp_f32_e32 v5, v193
	v_add_f32_e32 v1, v119, v1
	v_exp_f32_e32 v6, v190
	v_add_f32_e32 v1, v120, v1
	v_exp_f32_e32 v7, v191
	v_add_f32_e32 v1, v121, v1
	v_mfma_f32_32x32x16_bf16 v[82:97], v[8:11], v[174:177], v[82:97]
	v_cvt_pk_bf16_f32 v129, v126, v123
	v_exp_f32_e32 v126, v188
	v_add_f32_e32 v1, v4, v1
	v_cvt_pk_bf16_f32 v130, v122, v125
	v_cvt_pk_bf16_f32 v131, v124, v127
	v_exp_f32_e32 v127, v189
	v_add_f32_e32 v1, v5, v1
	v_mfma_f32_32x32x16_bf16 v[98:113], v[134:137], v[174:177], v[98:113]
	v_add_f32_e32 v1, v6, v1
	v_add_f32_e32 v1, v7, v1
	v_add_f32_e32 v1, v126, v1
	v_add_f32_e32 v1, v127, v1
	v_add_f32_e32 v1, v186, v1
	v_add_f32_e32 v1, v187, v1
	v_add_f32_e32 v1, v184, v1
	v_mfma_f32_32x32x16_bf16 v[82:97], v[12:15], v[170:173], v[82:97]
	v_add_f32_e32 v1, v185, v1
	v_add_f32_e32 v1, v182, v1
	v_add_f32_e32 v1, v183, v1
	v_add_f32_e32 v1, v180, v1
	v_add_f32_e32 v1, v181, v1
	v_add_f32_e32 v1, v178, v1
	v_add_f32_e32 v228, v179, v1
	v_mfma_f32_32x32x16_bf16 v[98:113], v[138:141], v[170:173], v[98:113]
	v_mov_b32_e32 v229, v228
	v_cvt_pk_bf16_f32 v122, v114, v115
	v_cvt_pk_bf16_f32 v123, v116, v117
	v_cvt_pk_bf16_f32 v124, v118, v119
	v_cvt_pk_bf16_f32 v125, v120, v121
	v_cvt_pk_bf16_f32 v116, v4, v5
	v_cvt_pk_bf16_f32 v117, v6, v7
	v_mfma_f32_32x32x16_bf16 v[82:97], v[142:145], v[166:169], v[82:97]
	v_cvt_pk_bf16_f32 v118, v126, v127
	v_cvt_pk_bf16_f32 v119, v186, v187
	s_nop 0
	v_permlane32_swap_b32_e32 v228, v229
	v_permlane32_swap_b32_e32 v116, v118
	v_permlane32_swap_b32_e32 v117, v119
	v_mfma_f32_32x32x16_bf16 v[98:113], v[194:197], v[166:169], v[98:113]
	v_cvt_pk_bf16_f32 v134, v184, v185
	v_cvt_pk_bf16_f32 v135, v182, v183
	v_cvt_pk_bf16_f32 v136, v180, v181
	v_cvt_pk_bf16_f32 v137, v178, v179
	v_permlane32_swap_b32_e32 v128, v130
	v_permlane32_swap_b32_e32 v129, v131
	v_mfma_f32_32x32x16_bf16 v[82:97], v[230:233], v[162:165], v[82:97]
	v_permlane32_swap_b32_e32 v122, v124
	v_permlane32_swap_b32_e32 v123, v125
	v_permlane32_swap_b32_e32 v134, v136
	v_permlane32_swap_b32_e32 v135, v137
	s_waitcnt lgkmcnt(0)
	v_mfma_f32_32x32x16_bf16 v[98:113], v[238:241], v[162:165], v[98:113]
	v_add_u32_e32 v6, 32, v2
	v_mov_b32_e32 v7, v3
	v_lshlrev_b64 v[12:13], 10, v[2:3]
	v_lshlrev_b64 v[14:15], 10, v[6:7]
	v_lshl_add_u64 v[4:5], v[16:17], 0, v[12:13]
	v_lshl_add_u64 v[8:9], v[16:17], 0, v[14:15]
	v_lshl_add_u64 v[12:13], v[206:207], 0, v[12:13]
	global_load_dwordx4 v[4:7], v[4:5], off
	s_nop 0
	global_load_dwordx4 v[8:11], v[8:9], off
	v_lshl_add_u64 v[114:115], v[206:207], 0, v[14:15]
	global_load_dwordx4 v[12:15], v[12:13], off
	s_nop 0
	global_load_dwordx4 v[178:181], v[114:115], off
	ds_read_b64_tr_b16 v[138:139], v213 offset:0
	ds_read_b64_tr_b16 v[140:141], v213 offset:0x800
	ds_read_b64_tr_b16 v[142:143], v213 offset:0x1000
	ds_read_b64_tr_b16 v[144:145], v213 offset:0x1800
	ds_read_b64_tr_b16 v[182:183], v213 offset:0x2000
	ds_read_b64_tr_b16 v[184:185], v213 offset:0x2800
	ds_read_b64_tr_b16 v[186:187], v213 offset:0x3000
	ds_read_b64_tr_b16 v[188:189], v213 offset:0x3800
	s_waitcnt lgkmcnt(0)
; __device__ __forceinline__ void mask_bits(f32x16& p0, f32x16& p1, unsigned long long mk, int hi) {
;     const float NEG = -__builtin_inff();
;     const unsigned lo = (unsigned)mk >> (4 * hi), hh = (unsigned)(mk >> 32) >> (4 * hi);
; #pragma unroll
;     for (int r = 0; r < 16; ++r) {
;         const int c = (r & 3) + 8 * (r >> 2);
;         if (!(lo & (1u << c))) p0[r] = NEG;
;         if (!(hh & (1u << c))) p1[r] = NEG;
;     }
; }
; __device__ __forceinline__ void partialSM(f32x16& p0, f32x16& p1, float& m_reg, float& mn, float& alpha) {
;     float pmax = p0[0];
; #pragma unroll
;     for (int r = 1; r < 16; ++r) pmax = fmaxf(pmax, p0[r]);
; #pragma unroll
;     for (int r = 0; r < 16; ++r) pmax = fmaxf(pmax, p1[r]);
;     { auto rr = __builtin_amdgcn_permlane32_swap(__float_as_uint(pmax), __float_as_uint(pmax), false, false);
;       pmax = fmaxf(__uint_as_float(rr[0]), __uint_as_float(rr[1])); }
;     constexpr float C2 = 1.4426950408889634f * SM_SCALE;
;     if (__builtin_expect(__all((pmax - m_reg) * SM_SCALE <= THR), 1)) { mn = m_reg; alpha = 1.f; }
; template <int VB>
; __device__ __forceinline__ void pv_tile(f32x16* o, int vb0, bf16x8 pa0, bf16x8 pa1, bf16x8 pa2, bf16x8 pa3) {
;     ...
;     PV_D0(0); PV_D0(1); PV_D0(2); PV_D0(3);
	s_nop 0
	v_mfma_f32_32x32x16_bf16 v[66:81], v[128:131], v[138:141], v[66:81]
	ds_read_b64_tr_b16 v[138:139], v213 offset:0x200
	ds_read_b64_tr_b16 v[140:141], v213 offset:0xa00
	v_mfma_f32_32x32x16_bf16 v[66:81], v[122:125], v[142:145], v[66:81]
	ds_read_b64_tr_b16 v[142:143], v213 offset:0x1200
	ds_read_b64_tr_b16 v[144:145], v213 offset:0x1a00
	v_mfma_f32_32x32x16_bf16 v[66:81], v[116:119], v[182:185], v[66:81]
	ds_read_b64_tr_b16 v[182:183], v213 offset:0x2200
	ds_read_b64_tr_b16 v[184:185], v213 offset:0x2a00
	ds_read_b64_tr_b16 v[190:191], v213 offset:0x3200
	ds_read_b64_tr_b16 v[192:193], v213 offset:0x3a00
	s_waitcnt lgkmcnt(0)
	v_mfma_f32_32x32x16_bf16 v[66:81], v[134:137], v[186:189], v[66:81]
	v_mfma_f32_32x32x16_bf16 v[50:65], v[128:131], v[138:141], v[50:65]
	ds_read_b64_tr_b16 v[138:139], v213 offset:0x400
	ds_read_b64_tr_b16 v[140:141], v213 offset:0xc00
	v_mfma_f32_32x32x16_bf16 v[50:65], v[122:125], v[142:145], v[50:65]
	ds_read_b64_tr_b16 v[142:143], v213 offset:0x1400
	ds_read_b64_tr_b16 v[144:145], v213 offset:0x1c00
	v_mfma_f32_32x32x16_bf16 v[50:65], v[116:119], v[182:185], v[50:65]
	ds_read_b64_tr_b16 v[182:183], v213 offset:0x2400
	ds_read_b64_tr_b16 v[184:185], v213 offset:0x2c00
	ds_read_b64_tr_b16 v[186:187], v213 offset:0x3400
	ds_read_b64_tr_b16 v[188:189], v213 offset:0x3c00
	s_waitcnt lgkmcnt(0)
	v_mfma_f32_32x32x16_bf16 v[50:65], v[134:137], v[190:193], v[50:65]
	v_mfma_f32_32x32x16_bf16 v[34:49], v[128:131], v[138:141], v[34:49]
	ds_read_b64_tr_b16 v[138:139], v213 offset:0x600
	ds_read_b64_tr_b16 v[140:141], v213 offset:0xe00
	v_mfma_f32_32x32x16_bf16 v[34:49], v[122:125], v[142:145], v[34:49]
	ds_read_b64_tr_b16 v[142:143], v213 offset:0x1600
	ds_read_b64_tr_b16 v[144:145], v213 offset:0x1e00
	v_mfma_f32_32x32x16_bf16 v[34:49], v[116:119], v[182:185], v[34:49]
	ds_read_b64_tr_b16 v[182:183], v213 offset:0x2600
	ds_read_b64_tr_b16 v[184:185], v213 offset:0x2e00
	ds_read_b64_tr_b16 v[190:191], v213 offset:0x3600
	ds_read_b64_tr_b16 v[192:193], v213 offset:0x3e00
	s_waitcnt lgkmcnt(0)
	v_mfma_f32_32x32x16_bf16 v[34:49], v[134:137], v[186:189], v[34:49]
	s_waitcnt vmcnt(4)
	v_lshrrev_b32_e32 v120, v215, v132
	v_lshrrev_b32_e32 v121, v215, v133
	v_mfma_f32_32x32x16_bf16 v[18:33], v[128:131], v[138:141], v[18:33]
	v_bfe_i32 v114, v120, 0, 1
	v_bfi_b32 v114, v114, v82, v225
	v_mov_b32_e32 v230, 1.0
	v_bfe_i32 v1, v121, 0, 1
	v_bfi_b32 v1, v1, v98, v225
	v_mfma_f32_32x32x16_bf16 v[18:33], v[122:125], v[142:145], v[18:33]
	v_bfe_i32 v98, v120, 1, 1
	v_bfi_b32 v98, v98, v83, v225
	v_bfe_i32 v82, v121, 1, 1
	v_bfi_b32 v82, v82, v99, v225
	v_mfma_f32_32x32x16_bf16 v[18:33], v[116:119], v[182:185], v[18:33]
	v_bfe_i32 v99, v120, 2, 1
	v_bfi_b32 v99, v99, v84, v225
	v_bfe_i32 v83, v121, 2, 1
	v_bfi_b32 v83, v83, v100, v225
	v_mfma_f32_32x32x16_bf16 v[18:33], v[134:137], v[190:193], v[18:33]
	v_bfe_i32 v100, v120, 3, 1
	v_bfi_b32 v100, v100, v85, v225
	v_bfe_i32 v84, v121, 3, 1
	v_bfi_b32 v84, v84, v101, v225
	v_bfe_i32 v101, v120, 8, 1
	v_bfi_b32 v101, v101, v86, v225
	v_bfe_i32 v85, v121, 8, 1
	v_bfi_b32 v85, v85, v102, v225
	v_bfe_i32 v102, v120, 9, 1
	v_bfi_b32 v102, v102, v87, v225
	v_bfe_i32 v86, v121, 9, 1
	v_bfi_b32 v86, v86, v103, v225
	v_bfe_i32 v103, v120, 10, 1
	v_bfi_b32 v103, v103, v88, v225
	v_bfe_i32 v87, v121, 10, 1
	v_bfi_b32 v87, v87, v104, v225
	v_and_b32_e32 v104, 0x2000000, v120
	v_bfe_i32 v115, v120, 11, 1
	v_bfi_b32 v115, v115, v89, v225
	v_bfe_i32 v88, v121, 11, 1
	v_bfi_b32 v88, v88, v105, v225
	v_and_b32_e32 v105, 0x4000000, v120
	v_bfe_i32 v116, v120, 16, 1
	v_bfi_b32 v116, v116, v90, v225
	v_bfe_i32 v89, v121, 16, 1
	v_bfi_b32 v89, v89, v106, v225
	v_and_b32_e32 v106, 0x8000000, v120
	v_bfe_i32 v117, v120, 17, 1
	v_bfi_b32 v117, v117, v91, v225
	v_bfe_i32 v90, v121, 17, 1
	v_bfi_b32 v90, v90, v107, v225
	v_bfe_i32 v107, v120, 18, 1
	v_bfi_b32 v107, v107, v92, v225
	v_bfe_i32 v91, v121, 18, 1
	v_bfi_b32 v91, v91, v108, v225
	v_bfe_i32 v108, v120, 19, 1
	v_bfi_b32 v108, v108, v93, v225
	v_and_b32_e32 v93, 0x1000000, v120
	v_bfe_i32 v92, v121, 19, 1
	v_bfi_b32 v92, v92, v109, v225
	v_cmp_ne_u32_e32 vcc, 0, v93
	v_max_f32_e32 v109, v98, v98
	s_nop 1
	v_cndmask_b32_e32 v94, v225, v94, vcc
	v_bfe_i32 v93, v121, 24, 1
	v_bfi_b32 v93, v93, v110, v225
	v_max_f32_e32 v110, v114, v114
	v_max_f32_e32 v109, v110, v109
	v_cmp_ne_u32_e32 vcc, 0, v104
	v_max3_f32 v109, v109, v99, v100
	s_nop 1
	v_cndmask_b32_e32 v95, v225, v95, vcc
	v_max3_f32 v109, v109, v101, v102
	v_max3_f32 v109, v109, v103, v115
	v_bfe_i32 v104, v121, 25, 1
	v_bfi_b32 v104, v104, v111, v225
	v_cmp_ne_u32_e32 vcc, 0, v105
	v_max3_f32 v109, v109, v116, v117
	s_nop 1
	v_cndmask_b32_e32 v96, v225, v96, vcc
	v_max3_f32 v109, v109, v107, v108
	v_max3_f32 v109, v109, v94, v95
	v_bfe_i32 v105, v121, 26, 1
	v_bfi_b32 v105, v105, v112, v225
	v_cmp_ne_u32_e32 vcc, 0, v106
	s_nop 0
	s_nop 1
	v_cndmask_b32_e32 v97, v225, v97, vcc
	v_max3_f32 v109, v109, v96, v97
	v_max3_f32 v109, v109, v1, v82
	v_max3_f32 v109, v109, v83, v84
	v_max3_f32 v109, v109, v85, v86
	v_max3_f32 v109, v109, v87, v88
	v_max3_f32 v109, v109, v89, v90
	v_max3_f32 v109, v109, v91, v92
	v_max3_f32 v109, v109, v93, v104
	v_bfe_i32 v106, v121, 27, 1
	v_bfi_b32 v106, v106, v113, v225
	v_max3_f32 v109, v109, v105, v106
	v_mov_b32_e32 v110, v109
	s_nop 1
	v_permlane32_swap_b32_e32 v109, v110
	v_max_f32_e32 v110, v110, v110
	v_max_f32_e32 v109, v109, v109
	v_max_f32_e32 v109, v109, v110
	v_sub_f32_e32 v110, v109, v201
	v_mul_f32_e32 v110, 0x3db504f3, v110
	v_cmp_ge_f32_e32 vcc, s41, v110
	s_cmp_eq_u64 vcc, exec
	s_cbranch_scc0 .LBB0_1241

; __device__ __forceinline__ void partialSM(f32x16& p0, f32x16& p1, float& m_reg, float& mn, float& alpha) {
;     ...
;     constexpr float C2 = 1.4426950408889634f * SM_SCALE;
;     if (__builtin_expect(__all((pmax - m_reg) * SM_SCALE <= THR), 1)) { mn = m_reg; alpha = 1.f; }
;     else { mn = fmaxf(m_reg, pmax); alpha = __builtin_amdgcn_exp2f((m_reg - mn) * C2); m_reg = mn; }
;     const float mnL = -mn * C2;
; #pragma unroll
;     for (int r = 0; r < 16; ++r) p0[r] = fmaf(p0[r], C2, mnL);
; #pragma unroll
;     for (int r = 0; r < 16; ++r) p1[r] = fmaf(p1[r], C2, mnL);
; #pragma unroll
;     for (int r = 0; r < 16; ++r) p0[r] = __builtin_amdgcn_exp2f(p0[r]);
; }
; __device__ __forceinline__ void finishSM(f32x16& p0, f32x16& p1, float alpha, float& l_reg, bf16x8& pa0, bf16x8& pa1, bf16x8& pa2, bf16x8& pa3) {
; #pragma unroll
;     for (int r = 0; r < 16; ++r) p1[r] = __builtin_amdgcn_exp2f(p1[r]);
;     float ps = 0;
; #pragma unroll
;     for (int r = 0; r < 16; ++r) ps += p0[r];
; #pragma unroll
;     for (int r = 0; r < 16; ++r) ps += p1[r];
;     { auto rr = __builtin_amdgcn_permlane32_swap(__float_as_uint(ps), __float_as_uint(ps), false, false);
;       ps = __uint_as_float(rr[0]) + __uint_as_float(rr[1]); }
; template <int KB, int MODE>
; __device__ __forceinline__ void qkt(f32x16& p0, f32x16& p1, const char* K_lds, int r32, int hi, const bf16x8* qr, float bz0, float bz1) {
;     p0 = f32x16{}; p1 = f32x16{};
;     if (MODE == 0) {
;         unsigned hm = (unsigned)hi - 1u; asm volatile("" : "+v"(hm));
;         u32x4 ow = {hm & 0x3f803f80u, hm & 0x00003f80u, 0u, 0u};
;         const bf16x8 ones = *reinterpret_cast<bf16x8*>(&ow);
;         p0 = __builtin_amdgcn_mfma_f32_32x32x16_bf16(bias_frag(bz0, hi), ones, p0, 0, 0, 0);
;         p1 = __builtin_amdgcn_mfma_f32_32x32x16_bf16(bias_frag(bz1, hi), ones, p1, 0, 0, 0);
;     }
;     const char* kb[4];
; #pragma unroll
;     for (int dd = 0; dd < 4; ++dd) kb[dd] = K_lds + KB * SHM_K + KSWZ(r32, (dd * 16 + hi * 8) * 2);
; #pragma unroll
;     for (int d0 = 0; d0 < 8; ++d0) { const char* a = kb[d0 & 3] + (d0 >> 2) * 128;
;         bf16x8 b0 = *reinterpret_cast<const bf16x8*>(a);
;         bf16x8 b1 = *reinterpret_cast<const bf16x8*>(a + 32 * 256);
;         p0 = __builtin_amdgcn_mfma_f32_32x32x16_bf16(b0, qr[d0], p0, 0, 0, 0);
;         p1 = __builtin_amdgcn_mfma_f32_32x32x16_bf16(b1, qr[d0], p1, 0, 0, 0); }
; }
.LBB0_1233:
	s_waitcnt lgkmcnt(0)
	s_barrier
	global_load_dwordx2 v[204:205], v[208:209], off offset:8
	v_mul_f32_e32 v210, 0xbe0293ee, v201
	v_fmamk_f32 v113, v114, 0x3e0293ee, v210
	v_fmamk_f32 v114, v98, 0x3e0293ee, v210
	v_fmamk_f32 v118, v99, 0x3e0293ee, v210
	v_fmamk_f32 v119, v100, 0x3e0293ee, v210
	v_fmamk_f32 v120, v101, 0x3e0293ee, v210
	v_fmamk_f32 v121, v102, 0x3e0293ee, v210
	v_fmamk_f32 v122, v103, 0x3e0293ee, v210
	v_fmamk_f32 v115, v115, 0x3e0293ee, v210
	v_fmamk_f32 v116, v116, 0x3e0293ee, v210
	v_fmamk_f32 v117, v117, 0x3e0293ee, v210
	v_fmamk_f32 v123, v107, 0x3e0293ee, v210
	v_fmamk_f32 v124, v108, 0x3e0293ee, v210
	v_fmamk_f32 v94, v94, 0x3e0293ee, v210
	v_fmamk_f32 v95, v95, 0x3e0293ee, v210
	v_fmamk_f32 v96, v96, 0x3e0293ee, v210
	v_fmamk_f32 v97, v97, 0x3e0293ee, v210
	v_fmamk_f32 v98, v1, 0x3e0293ee, v210
	v_fmamk_f32 v99, v82, 0x3e0293ee, v210
	v_fmamk_f32 v100, v83, 0x3e0293ee, v210
	v_fmamk_f32 v101, v84, 0x3e0293ee, v210
	v_fmamk_f32 v102, v85, 0x3e0293ee, v210
	v_fmamk_f32 v103, v86, 0x3e0293ee, v210
	v_fmamk_f32 v107, v87, 0x3e0293ee, v210
	v_fmamk_f32 v108, v88, 0x3e0293ee, v210
	v_fmamk_f32 v109, v89, 0x3e0293ee, v210
	v_fmamk_f32 v110, v90, 0x3e0293ee, v210
	v_fmamk_f32 v111, v91, 0x3e0293ee, v210
	v_fmamk_f32 v112, v92, 0x3e0293ee, v210
	v_fmamk_f32 v1, v93, 0x3e0293ee, v210
	v_exp_f32_e32 v82, v113
	v_exp_f32_e32 v83, v114
	v_exp_f32_e32 v84, v118
	v_exp_f32_e32 v85, v119
	v_exp_f32_e32 v86, v120
	v_exp_f32_e32 v87, v121
	v_exp_f32_e32 v88, v122
	v_exp_f32_e32 v89, v115
	v_exp_f32_e32 v90, v116
	v_exp_f32_e32 v91, v117
	v_exp_f32_e32 v92, v123
	v_exp_f32_e32 v93, v124
	v_exp_f32_e32 v94, v94
	v_exp_f32_e32 v95, v95
	v_exp_f32_e32 v96, v96
	v_exp_f32_e32 v97, v97
	v_fmamk_f32 v113, v104, 0x3e0293ee, v210
	v_fmamk_f32 v182, v105, 0x3e0293ee, v210
	v_fmamk_f32 v183, v106, 0x3e0293ee, v210
	ds_read_b128 v[114:117], v221 offset:32768
	ds_read_b128 v[118:121], v221 offset:40960
	ds_read_b128 v[184:187], v222 offset:32768
	ds_read_b128 v[188:191], v222 offset:40960
	v_exp_f32_e32 v104, v107
	v_exp_f32_e32 v107, v110
	s_waitcnt lgkmcnt(3)
	v_mfma_f32_32x32x16_bf16 v[130:145], v[114:117], v[158:161], 0
	v_exp_f32_e32 v110, v1
	v_add_f32_e32 v1, 0, v82
	v_add_f32_e32 v1, v83, v1
	v_add_f32_e32 v1, v84, v1
	v_add_f32_e32 v1, v85, v1
	v_add_f32_e32 v1, v86, v1
	v_add_f32_e32 v1, v87, v1
	s_waitcnt lgkmcnt(2)
	v_mfma_f32_32x32x16_bf16 v[114:129], v[118:121], v[158:161], 0
	v_add_f32_e32 v1, v88, v1
	v_add_f32_e32 v1, v89, v1
	v_add_f32_e32 v1, v90, v1
	v_add_f32_e32 v1, v91, v1
	v_add_f32_e32 v1, v92, v1
	v_add_f32_e32 v1, v93, v1
	v_exp_f32_e32 v98, v98
	s_waitcnt lgkmcnt(1)
	v_mfma_f32_32x32x16_bf16 v[130:145], v[184:187], v[154:157], v[130:145]
	v_add_f32_e32 v1, v94, v1
	v_exp_f32_e32 v99, v99
	v_add_f32_e32 v1, v95, v1
	v_exp_f32_e32 v100, v100
	v_add_f32_e32 v1, v96, v1
	v_exp_f32_e32 v101, v101
	v_add_f32_e32 v1, v97, v1
	s_waitcnt lgkmcnt(0)
	v_mfma_f32_32x32x16_bf16 v[114:129], v[188:191], v[154:157], v[114:129]
	ds_read_b128 v[184:187], v223 offset:32768
	ds_read_b128 v[188:191], v223 offset:40960
	v_exp_f32_e32 v102, v102
	v_add_f32_e32 v1, v98, v1
	v_exp_f32_e32 v103, v103
	v_add_f32_e32 v1, v99, v1
	v_add_f32_e32 v1, v100, v1
	v_exp_f32_e32 v105, v108
	s_waitcnt lgkmcnt(1)
	v_mfma_f32_32x32x16_bf16 v[130:145], v[184:187], v[150:153], v[130:145]
	v_add_f32_e32 v1, v101, v1
	v_exp_f32_e32 v106, v109
	v_add_f32_e32 v1, v102, v1
	v_add_f32_e32 v1, v103, v1
	v_exp_f32_e32 v108, v111
	v_add_f32_e32 v1, v104, v1
	v_exp_f32_e32 v109, v112
	s_waitcnt lgkmcnt(0)
	v_mfma_f32_32x32x16_bf16 v[114:129], v[188:191], v[150:153], v[114:129]
	ds_read_b128 v[184:187], v224 offset:32768
	ds_read_b128 v[188:191], v224 offset:40960
	v_add_f32_e32 v1, v105, v1
	v_add_f32_e32 v1, v106, v1
	v_exp_f32_e32 v111, v113
	v_add_f32_e32 v1, v107, v1
	v_exp_f32_e32 v112, v182
	v_add_f32_e32 v1, v108, v1
	s_waitcnt lgkmcnt(1)
	v_mfma_f32_32x32x16_bf16 v[130:145], v[184:187], v[146:149], v[130:145]
	v_exp_f32_e32 v113, v183
	v_add_f32_e32 v1, v109, v1
	v_add_f32_e32 v1, v110, v1
	v_add_f32_e32 v1, v111, v1
	v_add_f32_e32 v1, v112, v1
	v_add_f32_e32 v231, v113, v1
	v_mov_b32_e32 v232, v231
	s_waitcnt lgkmcnt(0)
	v_mfma_f32_32x32x16_bf16 v[114:129], v[188:191], v[146:149], v[114:129]
	v_xor_b32_e32 v184, 0x80, v221
	ds_read_b128 v[184:187], v184 offset:32768
	v_xor_b32_e32 v188, 0x80, v221
	ds_read_b128 v[188:191], v188 offset:40960
	v_permlane32_swap_b32_e32 v231, v232
	s_waitcnt lgkmcnt(1)
	v_mfma_f32_32x32x16_bf16 v[130:145], v[184:187], v[174:177], v[130:145]
	s_waitcnt lgkmcnt(0)
	v_mfma_f32_32x32x16_bf16 v[114:129], v[188:191], v[174:177], v[114:129]
	v_xor_b32_e32 v184, 0x80, v222
	ds_read_b128 v[184:187], v184 offset:32768
	v_xor_b32_e32 v188, 0x80, v222
	ds_read_b128 v[188:191], v188 offset:40960
	s_waitcnt lgkmcnt(1)
	v_mfma_f32_32x32x16_bf16 v[130:145], v[184:187], v[170:173], v[130:145]
	s_waitcnt lgkmcnt(0)
	v_mfma_f32_32x32x16_bf16 v[114:129], v[188:191], v[170:173], v[114:129]
	v_xor_b32_e32 v184, 0x80, v223
	ds_read_b128 v[184:187], v184 offset:32768
	v_xor_b32_e32 v188, 0x80, v223
	ds_read_b128 v[188:191], v188 offset:40960
	s_waitcnt lgkmcnt(1)
	v_mfma_f32_32x32x16_bf16 v[130:145], v[184:187], v[166:169], v[130:145]
	s_waitcnt lgkmcnt(0)
	v_mfma_f32_32x32x16_bf16 v[114:129], v[188:191], v[166:169], v[114:129]
	v_xor_b32_e32 v184, 0x80, v224
	ds_read_b128 v[184:187], v184 offset:32768
	v_xor_b32_e32 v188, 0x80, v224
	ds_read_b128 v[188:191], v188 offset:40960
	v_cvt_pk_bf16_f32 v182, v82, v83
	v_cvt_pk_bf16_f32 v183, v84, v85
	s_waitcnt lgkmcnt(1)
	v_mfma_f32_32x32x16_bf16 v[130:145], v[184:187], v[162:165], v[130:145]
	v_cvt_pk_bf16_f32 v184, v86, v87
	v_cvt_pk_bf16_f32 v185, v88, v89
	v_cvt_pk_bf16_f32 v186, v90, v91
	v_cvt_pk_bf16_f32 v187, v92, v93
	s_nop 0
	v_permlane32_swap_b32_e32 v182, v184
	s_waitcnt lgkmcnt(0)
	v_mfma_f32_32x32x16_bf16 v[114:129], v[188:191], v[162:165], v[114:129]
	v_cvt_pk_bf16_f32 v188, v94, v95
	v_cvt_pk_bf16_f32 v189, v96, v97
	v_cvt_pk_bf16_f32 v190, v98, v99
	v_cvt_pk_bf16_f32 v191, v100, v101
	v_cvt_pk_bf16_f32 v192, v102, v103
	v_cvt_pk_bf16_f32 v193, v104, v105
	v_cvt_pk_bf16_f32 v194, v106, v107
	v_cvt_pk_bf16_f32 v195, v108, v109
	v_cvt_pk_bf16_f32 v196, v110, v111
	v_cvt_pk_bf16_f32 v197, v112, v113
	v_permlane32_swap_b32_e32 v183, v185
	v_permlane32_swap_b32_e32 v186, v188
	v_permlane32_swap_b32_e32 v187, v189
	v_permlane32_swap_b32_e32 v190, v192
	v_permlane32_swap_b32_e32 v191, v193
	v_permlane32_swap_b32_e32 v194, v196
	v_permlane32_swap_b32_e32 v195, v197
	s_add_i32 s26, s21, 1
	s_cmp_lt_i32 s26, s20
	s_cselect_b64 s[24:25], -1, 0
	s_cmp_ge_i32 s26, s20
	s_cbranch_scc1 .LBB0_1235
	v_add_u32_e32 v4, 64, v2
	v_mov_b32_e32 v5, v3
	v_add_u32_e32 v6, 0x60, v2
	v_mov_b32_e32 v7, v3
	v_lshlrev_b64 v[12:13], 10, v[4:5]
	v_lshlrev_b64 v[14:15], 10, v[6:7]
	v_lshl_add_u64 v[4:5], v[16:17], 0, v[12:13]
	v_lshl_add_u64 v[8:9], v[16:17], 0, v[14:15]
	v_lshl_add_u64 v[12:13], v[206:207], 0, v[12:13]
	v_lshl_add_u64 v[178:179], v[206:207], 0, v[14:15]
	global_load_dwordx4 v[4:7], v[4:5], off
	s_nop 0
	global_load_dwordx4 v[8:11], v[8:9], off
	s_nop 0
	global_load_dwordx4 v[12:15], v[12:13], off
	s_nop 0
	global_load_dwordx4 v[178:181], v[178:179], off

; #define SBAR() do { asm volatile("s_waitcnt vmcnt(0) lgkmcnt(0)" ::: "memory"); __syncthreads(); } while (0)
; #define SBAR() __builtin_amdgcn_sched_barrier(0)
; #define MLOAD_(t, off) do { if (MODE == 1) mk = *(const unsigned long long*)((const char*)(cur.msk + (t)) + (off)); } while (0)
; template <int KB, int MODE>
; __device__ __forceinline__ void qkt(f32x16& p0, f32x16& p1, const char* K_lds, int r32, int hi, const bf16x8* qr, float bz0, float bz1) {
;     p0 = f32x16{}; p1 = f32x16{};
;     if (MODE == 0) {
;         unsigned hm = (unsigned)hi - 1u; asm volatile("" : "+v"(hm));
;         u32x4 ow = {hm & 0x3f803f80u, hm & 0x00003f80u, 0u, 0u};
;         const bf16x8 ones = *reinterpret_cast<bf16x8*>(&ow);
;         p0 = __builtin_amdgcn_mfma_f32_32x32x16_bf16(bias_frag(bz0, hi), ones, p0, 0, 0, 0);
;         p1 = __builtin_amdgcn_mfma_f32_32x32x16_bf16(bias_frag(bz1, hi), ones, p1, 0, 0, 0);
;     }
;     const char* kb[4];
; #pragma unroll
;     for (int dd = 0; dd < 4; ++dd) kb[dd] = K_lds + KB * SHM_K + KSWZ(r32, (dd * 16 + hi * 8) * 2);
; #pragma unroll
;     for (int d0 = 0; d0 < 8; ++d0) { const char* a = kb[d0 & 3] + (d0 >> 2) * 128;
;         bf16x8 b0 = *reinterpret_cast<const bf16x8*>(a);
;         bf16x8 b1 = *reinterpret_cast<const bf16x8*>(a + 32 * 256);
;         p0 = __builtin_amdgcn_mfma_f32_32x32x16_bf16(b0, qr[d0], p0, 0, 0, 0);
;         p1 = __builtin_amdgcn_mfma_f32_32x32x16_bf16(b1, qr[d0], p1, 0, 0, 0); }
; }
; template <int MODE>
; __device__ __forceinline__ void block(const Ref& cur, const Ref& nxt, char* lds, Seam& S) {
;     ...
;     const bool even = (NT & 1) == 0;
;     constexpr bool QPRE = (MODE == 1);
;     int tid2 = tid; asm volatile("" : "+v"(tid2));
;     const int lane2 = tid2 & 63, r32e = lane2 & 31, hie = lane2 >> 5, sre = tid2 >> 4, sce = (tid2 & 15) * 8;
;     const unsigned moffe = (unsigned)((wid * 4 + (r32e >> 3)) * 64 * 8);
;     if (even) { MLOAD_(NT - 1, moffe); SBAR(); qkt<1, MODE>(pB0, pB1, K_lds, r32, hi, S.qr, bz0, bz1); SBAR(); }
.LBB0_1245:
	s_bitcmp0_b32 s20, 0
	s_cselect_b64 s[24:25], -1, 0
	v_mov_b32_e32 v17, v0
	s_and_b64 vcc, exec, s[24:25]
	v_and_b32_e32 v16, 31, v17
	s_cbranch_vccz .LBB0_1247
	s_ashr_i32 s21, s20, 31
	v_lshrrev_b32_e32 v2, 3, v16
	s_lshl_b64 s[20:21], s[20:21], 3
	v_or_b32_e32 v2, s6, v2
	s_add_u32 s20, s22, s20
	v_lshlrev_b32_e32 v2, 9, v2
	s_addc_u32 s21, s23, s21
	global_load_dwordx2 v[204:205], v2, s[20:21] offset:-8
	ds_read_b128 v[4:7], v221 offset:49152
	v_xor_b32_e32 v8, 0x80, v221
	ds_read_b128 v[8:11], v8 offset:49152
	s_waitcnt lgkmcnt(1)
	v_mfma_f32_32x32x16_bf16 v[82:97], v[4:7], v[158:161], 0
	ds_read_b128 v[4:7], v221 offset:57344
	v_xor_b32_e32 v12, 0x80, v221
	ds_read_b128 v[12:15], v12 offset:57344
	s_waitcnt lgkmcnt(1)
	v_mfma_f32_32x32x16_bf16 v[98:113], v[4:7], v[158:161], 0
	ds_read_b128 v[4:7], v222 offset:49152
	v_xor_b32_e32 v130, 0x80, v222
	ds_read_b128 v[130:133], v130 offset:49152
	s_waitcnt lgkmcnt(1)
	v_mfma_f32_32x32x16_bf16 v[82:97], v[4:7], v[154:157], v[82:97]
	ds_read_b128 v[4:7], v222 offset:57344
	v_xor_b32_e32 v134, 0x80, v222
	ds_read_b128 v[134:137], v134 offset:57344
	s_waitcnt lgkmcnt(1)
	v_mfma_f32_32x32x16_bf16 v[98:113], v[4:7], v[154:157], v[98:113]
	ds_read_b128 v[4:7], v223 offset:49152
	v_xor_b32_e32 v138, 0x80, v223
	ds_read_b128 v[138:141], v138 offset:49152
	s_waitcnt lgkmcnt(1)
	v_mfma_f32_32x32x16_bf16 v[82:97], v[4:7], v[150:153], v[82:97]
	ds_read_b128 v[4:7], v223 offset:57344
	v_xor_b32_e32 v142, 0x80, v223
	ds_read_b128 v[142:145], v142 offset:57344
	s_waitcnt lgkmcnt(1)
	v_mfma_f32_32x32x16_bf16 v[98:113], v[4:7], v[150:153], v[98:113]
	ds_read_b128 v[4:7], v224 offset:49152
	v_xor_b32_e32 v150, 0x80, v224
	ds_read_b128 v[150:153], v150 offset:49152
	s_waitcnt lgkmcnt(1)
	v_mfma_f32_32x32x16_bf16 v[82:97], v[4:7], v[146:149], v[82:97]
	ds_read_b128 v[4:7], v224 offset:57344
	v_xor_b32_e32 v154, 0x80, v224
	ds_read_b128 v[154:157], v154 offset:57344
	s_waitcnt lgkmcnt(1)
	v_mfma_f32_32x32x16_bf16 v[98:113], v[4:7], v[146:149], v[98:113]
	v_mfma_f32_32x32x16_bf16 v[82:97], v[8:11], v[174:177], v[82:97]
	v_mfma_f32_32x32x16_bf16 v[98:113], v[12:15], v[174:177], v[98:113]
	v_mfma_f32_32x32x16_bf16 v[82:97], v[130:133], v[170:173], v[82:97]
	v_mfma_f32_32x32x16_bf16 v[98:113], v[134:137], v[170:173], v[98:113]
	v_mfma_f32_32x32x16_bf16 v[82:97], v[138:141], v[166:169], v[82:97]
	v_mfma_f32_32x32x16_bf16 v[98:113], v[142:145], v[166:169], v[98:113]
	v_mfma_f32_32x32x16_bf16 v[82:97], v[150:153], v[162:165], v[82:97]
	s_waitcnt lgkmcnt(0)
	v_mfma_f32_32x32x16_bf16 v[98:113], v[154:157], v[162:165], v[98:113]
